# one static s_setprio 1 for waves 4-7 at kernel entry; the per-segment priority flips around the MFMA clusters of all GEMM loops removed
# baseline (speedup 1.0000x reference)
_Z8mega_fwd6Params:
	s_load_dwordx4 s[24:27], s[0:1], 0x80
	s_add_u32 s6, s0, 0x88
	s_mov_b32 s64, s2
	s_addc_u32 s7, s1, 0
	v_and_b32_e32 v218, 0x3ff, v0
	s_waitcnt lgkmcnt(0)
	s_and_b32 s2, s26, 7
	v_readfirstlane_b32 s3, v218
	s_cmp_lt_u32 s3, 0x100
	s_cbranch_scc1 .Lprio_skip
	s_setprio 1
.Lprio_skip:
	s_cmp_lg_u32 s2, 0
	s_mov_b32 s20, s64
	s_cbranch_scc0 .LBB0_132
	s_load_dword s2, s[0:1], 0x90
	v_cmp_gt_u32_e32 vcc, 16, v218
	s_and_saveexec_b64 s[4:5], vcc

.LBB0_193:
	s_add_u32 s8, s66, 0xfffc0080
	s_addc_u32 s9, s67, -1
	s_add_i32 s56, 0, 0x10000
	s_cmp_eq_u32 s91, 12
	s_cselect_b32 s75, s31, s9
	s_cselect_b32 s74, s87, s8
	v_add_u32_e32 v148, s56, v151
	s_cselect_b32 s73, s21, s90
	s_cselect_b32 s72, s88, s89
	s_add_i32 s57, 0, 0x14000
	ds_read_b128 v[140:143], v148
	ds_read_b128 v[144:147], v148 offset:1024
	ds_read_b128 v[154:157], v148 offset:2048
	ds_read_b128 v[158:161], v148 offset:3072
	v_add_u32_e32 v148, s57, v151
	ds_read_b128 v[162:165], v148
	ds_read_b128 v[166:169], v148 offset:1024
	ds_read_b128 v[170:173], v148 offset:2048
	ds_read_b128 v[174:177], v148 offset:3072
	v_lshl_add_u64 v[148:149], s[66:67], 0, v[136:137]
	s_add_i32 m0, s28, 0xc000
	ds_read_b128 v[182:185], v153
	ds_read_b128 v[186:189], v153 offset:1024
	ds_read_b128 v[190:193], v153 offset:2048
	ds_read_b128 v[194:197], v153 offset:3072
	ds_read_b128 v[198:201], v153 offset:4096
	ds_read_b128 v[202:205], v153 offset:5120
	ds_read_b128 v[206:209], v153 offset:6144
	ds_read_b128 v[210:213], v153 offset:7168
	global_load_lds_dwordx4 v[148:149], off
	v_lshl_add_u64 v[148:149], s[66:67], 0, v[138:139]
	s_add_i32 m0, s28, 0xe000
	s_nop 0
	global_load_lds_dwordx4 v[148:149], off
	s_waitcnt vmcnt(8)
	s_waitcnt lgkmcnt(0)
	s_barrier
	s_waitcnt lgkmcnt(0)
	v_mfma_f32_16x16x32_bf16 v[126:129], v[140:143], v[182:185], v[126:129]
	v_mfma_f32_16x16x32_bf16 v[122:125], v[154:157], v[182:185], v[122:125]
	v_mfma_f32_16x16x32_bf16 v[110:113], v[140:143], v[190:193], v[110:113]
	v_mfma_f32_16x16x32_bf16 v[106:109], v[154:157], v[190:193], v[106:109]
	v_mfma_f32_16x16x32_bf16 v[94:97], v[140:143], v[198:201], v[94:97]
	v_mfma_f32_16x16x32_bf16 v[90:93], v[154:157], v[198:201], v[90:93]
	v_mfma_f32_16x16x32_bf16 v[78:81], v[140:143], v[206:209], v[78:81]
	v_mfma_f32_16x16x32_bf16 v[74:77], v[154:157], v[206:209], v[74:77]
	v_mfma_f32_16x16x32_bf16 v[126:129], v[144:147], v[186:189], v[126:129]
	v_mfma_f32_16x16x32_bf16 v[122:125], v[158:161], v[186:189], v[122:125]
	v_mfma_f32_16x16x32_bf16 v[110:113], v[144:147], v[194:197], v[110:113]
	v_mfma_f32_16x16x32_bf16 v[106:109], v[158:161], v[194:197], v[106:109]
	v_mfma_f32_16x16x32_bf16 v[94:97], v[144:147], v[202:205], v[94:97]
	v_mfma_f32_16x16x32_bf16 v[90:93], v[158:161], v[202:205], v[90:93]
	v_mfma_f32_16x16x32_bf16 v[78:81], v[144:147], v[210:213], v[78:81]
	v_mfma_f32_16x16x32_bf16 v[74:77], v[158:161], v[210:213], v[74:77]
	v_mfma_f32_16x16x32_bf16 v[118:121], v[162:165], v[182:185], v[118:121]
	v_mfma_f32_16x16x32_bf16 v[114:117], v[170:173], v[182:185], v[114:117]
	v_mfma_f32_16x16x32_bf16 v[102:105], v[162:165], v[190:193], v[102:105]
	v_mfma_f32_16x16x32_bf16 v[98:101], v[170:173], v[190:193], v[98:101]
	v_mfma_f32_16x16x32_bf16 v[86:89], v[162:165], v[198:201], v[86:89]
	v_mfma_f32_16x16x32_bf16 v[82:85], v[170:173], v[198:201], v[82:85]
	v_mfma_f32_16x16x32_bf16 v[70:73], v[162:165], v[206:209], v[70:73]
	v_mfma_f32_16x16x32_bf16 v[66:69], v[170:173], v[206:209], v[66:69]
	v_mfma_f32_16x16x32_bf16 v[118:121], v[166:169], v[186:189], v[118:121]
	v_mfma_f32_16x16x32_bf16 v[114:117], v[174:177], v[186:189], v[114:117]
	v_mfma_f32_16x16x32_bf16 v[102:105], v[166:169], v[194:197], v[102:105]
	v_mfma_f32_16x16x32_bf16 v[98:101], v[174:177], v[194:197], v[98:101]
	v_mfma_f32_16x16x32_bf16 v[86:89], v[166:169], v[202:205], v[86:89]
	v_mfma_f32_16x16x32_bf16 v[82:85], v[174:177], v[202:205], v[82:85]
	v_mfma_f32_16x16x32_bf16 v[70:73], v[166:169], v[210:213], v[70:73]
	v_mfma_f32_16x16x32_bf16 v[66:69], v[174:177], v[210:213], v[66:69]
	s_barrier
	s_add_i32 s8, s56, s2
	v_lshl_add_u64 v[148:149], s[72:73], 0, v[32:33]
	s_mov_b32 m0, s8
	ds_read_b128 v[182:185], v153 offset:16384
	ds_read_b128 v[186:189], v153 offset:17408
	ds_read_b128 v[190:193], v153 offset:18432
	ds_read_b128 v[194:197], v153 offset:19456
	ds_read_b128 v[198:201], v153 offset:20480
	ds_read_b128 v[202:205], v153 offset:21504
	ds_read_b128 v[206:209], v153 offset:22528
	ds_read_b128 v[210:213], v153 offset:23552
	global_load_lds_dwordx4 v[148:149], off
	s_add_i32 m0, s8, 0x2000
	s_add_u32 s8, s72, 0x40000
	v_lshl_add_u64 v[178:179], s[72:73], 0, v[134:135]
	s_addc_u32 s9, s73, 0
	s_add_i32 s56, s57, s2
	global_load_lds_dwordx4 v[178:179], off
	v_lshl_add_u64 v[214:215], s[8:9], 0, v[32:33]
	s_mov_b32 m0, s56
	v_lshl_add_u64 v[216:217], s[74:75], 0, v[132:133]
	global_load_lds_dwordx4 v[214:215], off
	v_lshl_add_u64 v[214:215], s[8:9], 0, v[134:135]
	s_add_i32 m0, s56, 0x2000
	s_nop 0
	global_load_lds_dwordx4 v[214:215], off
	v_lshl_add_u64 v[214:215], s[74:75], 0, v[130:131]
	s_mov_b32 m0, s28
	s_nop 0
	global_load_lds_dwordx4 v[214:215], off
	s_mov_b32 m0, s76
	s_nop 0
	global_load_lds_dwordx4 v[216:217], off
	s_waitcnt vmcnt(8)
	s_waitcnt lgkmcnt(0)
	s_barrier
	s_waitcnt lgkmcnt(0)
	v_mfma_f32_16x16x32_bf16 v[62:65], v[140:143], v[182:185], v[62:65]
	v_mfma_f32_16x16x32_bf16 v[58:61], v[154:157], v[182:185], v[58:61]
	v_mfma_f32_16x16x32_bf16 v[46:49], v[140:143], v[190:193], v[46:49]
	v_mfma_f32_16x16x32_bf16 v[42:45], v[154:157], v[190:193], v[42:45]
	v_mfma_f32_16x16x32_bf16 v[28:31], v[140:143], v[198:201], v[28:31]
	v_mfma_f32_16x16x32_bf16 v[24:27], v[154:157], v[198:201], v[24:27]
	v_mfma_f32_16x16x32_bf16 v[12:15], v[140:143], v[206:209], v[12:15]
	v_mfma_f32_16x16x32_bf16 v[8:11], v[154:157], v[206:209], v[8:11]
	v_mfma_f32_16x16x32_bf16 v[62:65], v[144:147], v[186:189], v[62:65]
	v_mfma_f32_16x16x32_bf16 v[58:61], v[158:161], v[186:189], v[58:61]
	v_mfma_f32_16x16x32_bf16 v[46:49], v[144:147], v[194:197], v[46:49]
	v_mfma_f32_16x16x32_bf16 v[42:45], v[158:161], v[194:197], v[42:45]
	v_mfma_f32_16x16x32_bf16 v[28:31], v[144:147], v[202:205], v[28:31]
	v_mfma_f32_16x16x32_bf16 v[24:27], v[158:161], v[202:205], v[24:27]
	v_mfma_f32_16x16x32_bf16 v[12:15], v[144:147], v[210:213], v[12:15]
	v_mfma_f32_16x16x32_bf16 v[8:11], v[158:161], v[210:213], v[8:11]
	v_mfma_f32_16x16x32_bf16 v[54:57], v[162:165], v[182:185], v[54:57]
	v_mfma_f32_16x16x32_bf16 v[50:53], v[170:173], v[182:185], v[50:53]
	v_mfma_f32_16x16x32_bf16 v[38:41], v[162:165], v[190:193], v[38:41]
	v_mfma_f32_16x16x32_bf16 v[34:37], v[170:173], v[190:193], v[34:37]
	v_mfma_f32_16x16x32_bf16 v[20:23], v[162:165], v[198:201], v[20:23]
	v_mfma_f32_16x16x32_bf16 v[16:19], v[170:173], v[198:201], v[16:19]
	v_mfma_f32_16x16x32_bf16 v[4:7], v[162:165], v[206:209], v[4:7]
	v_mfma_f32_16x16x32_bf16 v[0:3], v[170:173], v[206:209], v[0:3]
	v_mfma_f32_16x16x32_bf16 v[54:57], v[166:169], v[186:189], v[54:57]
	v_mfma_f32_16x16x32_bf16 v[50:53], v[174:177], v[186:189], v[50:53]
	v_mfma_f32_16x16x32_bf16 v[38:41], v[166:169], v[194:197], v[38:41]
	v_mfma_f32_16x16x32_bf16 v[34:37], v[174:177], v[194:197], v[34:37]
	v_mfma_f32_16x16x32_bf16 v[20:23], v[166:169], v[202:205], v[20:23]
	v_mfma_f32_16x16x32_bf16 v[16:19], v[174:177], v[202:205], v[16:19]
	v_mfma_f32_16x16x32_bf16 v[4:7], v[166:169], v[210:213], v[4:7]
	v_mfma_f32_16x16x32_bf16 v[0:3], v[174:177], v[210:213], v[0:3]
	s_barrier
	s_add_i32 s56, 0, 0x18000
	s_add_i32 s57, 0, 0x1c000
	v_add_u32_e32 v158, s56, v151
	v_add_u32_e32 v174, s57, v151
	ds_read_b128 v[140:143], v158
	ds_read_b128 v[144:147], v158 offset:1024
	ds_read_b128 v[154:157], v158 offset:2048
	ds_read_b128 v[158:161], v158 offset:3072
	ds_read_b128 v[162:165], v174
	ds_read_b128 v[166:169], v174 offset:1024
	ds_read_b128 v[170:173], v174 offset:2048
	ds_read_b128 v[174:177], v174 offset:3072
	s_add_u32 s8, s74, 0x40000
	s_addc_u32 s9, s75, 0
	s_mov_b32 m0, s77
	v_lshl_add_u64 v[228:229], s[8:9], 0, v[130:131]
	ds_read_b128 v[182:185], v153 offset:32768
	ds_read_b128 v[186:189], v153 offset:33792
	ds_read_b128 v[190:193], v153 offset:34816
	ds_read_b128 v[194:197], v153 offset:35840
	ds_read_b128 v[198:201], v153 offset:36864
	ds_read_b128 v[202:205], v153 offset:37888
	ds_read_b128 v[206:209], v153 offset:38912
	ds_read_b128 v[210:213], v153 offset:39936
	global_load_lds_dwordx4 v[228:229], off
	v_lshl_add_u64 v[228:229], s[8:9], 0, v[132:133]
	s_mov_b32 m0, s83
	s_nop 0
	global_load_lds_dwordx4 v[228:229], off
	s_waitcnt vmcnt(8)
	s_waitcnt lgkmcnt(0)
	s_barrier
	s_waitcnt lgkmcnt(0)
	v_mfma_f32_16x16x32_bf16 v[126:129], v[140:143], v[182:185], v[126:129]
	v_mfma_f32_16x16x32_bf16 v[122:125], v[154:157], v[182:185], v[122:125]
	v_mfma_f32_16x16x32_bf16 v[110:113], v[140:143], v[190:193], v[110:113]
	v_mfma_f32_16x16x32_bf16 v[106:109], v[154:157], v[190:193], v[106:109]
	v_mfma_f32_16x16x32_bf16 v[94:97], v[140:143], v[198:201], v[94:97]
	v_mfma_f32_16x16x32_bf16 v[90:93], v[154:157], v[198:201], v[90:93]
	v_mfma_f32_16x16x32_bf16 v[78:81], v[140:143], v[206:209], v[78:81]
	v_mfma_f32_16x16x32_bf16 v[74:77], v[154:157], v[206:209], v[74:77]
	v_mfma_f32_16x16x32_bf16 v[126:129], v[144:147], v[186:189], v[126:129]
	v_mfma_f32_16x16x32_bf16 v[122:125], v[158:161], v[186:189], v[122:125]
	v_mfma_f32_16x16x32_bf16 v[110:113], v[144:147], v[194:197], v[110:113]
	v_mfma_f32_16x16x32_bf16 v[106:109], v[158:161], v[194:197], v[106:109]
	v_mfma_f32_16x16x32_bf16 v[94:97], v[144:147], v[202:205], v[94:97]
	v_mfma_f32_16x16x32_bf16 v[90:93], v[158:161], v[202:205], v[90:93]
	v_mfma_f32_16x16x32_bf16 v[78:81], v[144:147], v[210:213], v[78:81]
	v_mfma_f32_16x16x32_bf16 v[74:77], v[158:161], v[210:213], v[74:77]
	v_mfma_f32_16x16x32_bf16 v[118:121], v[162:165], v[182:185], v[118:121]
	v_mfma_f32_16x16x32_bf16 v[114:117], v[170:173], v[182:185], v[114:117]
	v_mfma_f32_16x16x32_bf16 v[102:105], v[162:165], v[190:193], v[102:105]
	v_mfma_f32_16x16x32_bf16 v[98:101], v[170:173], v[190:193], v[98:101]
	v_mfma_f32_16x16x32_bf16 v[86:89], v[162:165], v[198:201], v[86:89]
	v_mfma_f32_16x16x32_bf16 v[82:85], v[170:173], v[198:201], v[82:85]
	v_mfma_f32_16x16x32_bf16 v[70:73], v[162:165], v[206:209], v[70:73]
	v_mfma_f32_16x16x32_bf16 v[66:69], v[170:173], v[206:209], v[66:69]
	v_mfma_f32_16x16x32_bf16 v[118:121], v[166:169], v[186:189], v[118:121]
	v_mfma_f32_16x16x32_bf16 v[114:117], v[174:177], v[186:189], v[114:117]
	v_mfma_f32_16x16x32_bf16 v[102:105], v[166:169], v[194:197], v[102:105]
	v_mfma_f32_16x16x32_bf16 v[98:101], v[174:177], v[194:197], v[98:101]
	v_mfma_f32_16x16x32_bf16 v[86:89], v[166:169], v[202:205], v[86:89]
	v_mfma_f32_16x16x32_bf16 v[82:85], v[174:177], v[202:205], v[82:85]
	v_mfma_f32_16x16x32_bf16 v[70:73], v[166:169], v[210:213], v[70:73]
	v_mfma_f32_16x16x32_bf16 v[66:69], v[174:177], v[210:213], v[66:69]
	s_barrier
	s_add_i32 s8, s56, s2
	v_lshl_add_u64 v[148:149], v[148:149], 0, s[38:39]
	s_mov_b32 m0, s8
	ds_read_b128 v[182:185], v153 offset:49152
	ds_read_b128 v[186:189], v153 offset:50176
	ds_read_b128 v[190:193], v153 offset:51200
	ds_read_b128 v[194:197], v153 offset:52224
	ds_read_b128 v[198:201], v153 offset:53248
	ds_read_b128 v[202:205], v153 offset:54272
	ds_read_b128 v[206:209], v153 offset:55296
	ds_read_b128 v[210:213], v153 offset:56320
	global_load_lds_dwordx4 v[148:149], off
	s_add_i32 m0, s8, 0x2000
	s_add_u32 s8, s72, 0x40080
	v_lshl_add_u64 v[148:149], v[178:179], 0, s[38:39]
	s_addc_u32 s9, s73, 0
	s_add_i32 s56, s57, s2
	global_load_lds_dwordx4 v[148:149], off
	v_lshl_add_u64 v[148:149], s[8:9], 0, v[32:33]
	s_mov_b32 m0, s56
	s_nop 0
	global_load_lds_dwordx4 v[148:149], off
	v_lshl_add_u64 v[148:149], s[8:9], 0, v[134:135]
	s_add_i32 m0, s56, 0x2000
	s_nop 0
	global_load_lds_dwordx4 v[148:149], off
	v_lshl_add_u64 v[148:149], v[214:215], 0, s[38:39]
	s_mov_b32 m0, s84
	s_nop 0
	global_load_lds_dwordx4 v[148:149], off
	v_lshl_add_u64 v[148:149], v[216:217], 0, s[38:39]
	s_mov_b32 m0, s85
	s_nop 0
	global_load_lds_dwordx4 v[148:149], off
	s_waitcnt vmcnt(8)
	s_waitcnt lgkmcnt(0)
	s_barrier
	s_waitcnt lgkmcnt(0)
	v_mfma_f32_16x16x32_bf16 v[62:65], v[140:143], v[182:185], v[62:65]
	v_mfma_f32_16x16x32_bf16 v[58:61], v[154:157], v[182:185], v[58:61]
	v_mfma_f32_16x16x32_bf16 v[46:49], v[140:143], v[190:193], v[46:49]
	v_mfma_f32_16x16x32_bf16 v[42:45], v[154:157], v[190:193], v[42:45]
	v_mfma_f32_16x16x32_bf16 v[28:31], v[140:143], v[198:201], v[28:31]
	v_mfma_f32_16x16x32_bf16 v[24:27], v[154:157], v[198:201], v[24:27]
	v_mfma_f32_16x16x32_bf16 v[12:15], v[140:143], v[206:209], v[12:15]
	v_mfma_f32_16x16x32_bf16 v[8:11], v[154:157], v[206:209], v[8:11]
	v_mfma_f32_16x16x32_bf16 v[62:65], v[144:147], v[186:189], v[62:65]
	v_mfma_f32_16x16x32_bf16 v[58:61], v[158:161], v[186:189], v[58:61]
	v_mfma_f32_16x16x32_bf16 v[46:49], v[144:147], v[194:197], v[46:49]
	v_mfma_f32_16x16x32_bf16 v[42:45], v[158:161], v[194:197], v[42:45]
	v_mfma_f32_16x16x32_bf16 v[28:31], v[144:147], v[202:205], v[28:31]
	v_mfma_f32_16x16x32_bf16 v[24:27], v[158:161], v[202:205], v[24:27]
	v_mfma_f32_16x16x32_bf16 v[12:15], v[144:147], v[210:213], v[12:15]
	v_mfma_f32_16x16x32_bf16 v[8:11], v[158:161], v[210:213], v[8:11]
	v_mfma_f32_16x16x32_bf16 v[54:57], v[162:165], v[182:185], v[54:57]
	v_mfma_f32_16x16x32_bf16 v[50:53], v[170:173], v[182:185], v[50:53]
	v_mfma_f32_16x16x32_bf16 v[38:41], v[162:165], v[190:193], v[38:41]
	v_mfma_f32_16x16x32_bf16 v[34:37], v[170:173], v[190:193], v[34:37]
	v_mfma_f32_16x16x32_bf16 v[20:23], v[162:165], v[198:201], v[20:23]
	v_mfma_f32_16x16x32_bf16 v[16:19], v[170:173], v[198:201], v[16:19]
	v_mfma_f32_16x16x32_bf16 v[4:7], v[162:165], v[206:209], v[4:7]
	v_mfma_f32_16x16x32_bf16 v[0:3], v[170:173], v[206:209], v[0:3]
	v_mfma_f32_16x16x32_bf16 v[54:57], v[166:169], v[186:189], v[54:57]
	v_mfma_f32_16x16x32_bf16 v[50:53], v[174:177], v[186:189], v[50:53]
	v_mfma_f32_16x16x32_bf16 v[38:41], v[166:169], v[194:197], v[38:41]
	v_mfma_f32_16x16x32_bf16 v[34:37], v[174:177], v[194:197], v[34:37]
	v_mfma_f32_16x16x32_bf16 v[20:23], v[166:169], v[202:205], v[20:23]
	v_mfma_f32_16x16x32_bf16 v[16:19], v[174:177], v[202:205], v[16:19]
	v_mfma_f32_16x16x32_bf16 v[4:7], v[166:169], v[210:213], v[4:7]
	v_mfma_f32_16x16x32_bf16 v[0:3], v[174:177], v[210:213], v[0:3]
	s_barrier
	s_add_i32 s91, s91, 2
	s_add_u32 s66, s66, 0x100
	s_addc_u32 s67, s67, 0
	s_add_u32 s89, s89, 0x100
	s_addc_u32 s90, s90, 0
	s_cmp_gt_u32 s91, 13
	s_cbranch_scc0 .LBB0_193
	v_readlane_b32 s88, v254, 63
	s_and_b64 vcc, exec, s[16:17]
	v_readlane_b32 s89, v255, 0
	s_cbranch_vccz .LBB0_196
	s_barrier

.LBB0_212:
	s_add_u32 s9, s10, 0xfffe0080
	s_addc_u32 s56, s11, -1
	s_add_i32 s8, 0, 0x10000
	s_cmp_eq_u32 s94, 4
	s_cselect_b32 s75, s31, s56
	s_cselect_b32 s74, s90, s9
	s_cselect_b32 s73, s35, s93
	s_cselect_b32 s72, s91, s92
	s_add_i32 s9, 0, 0x14000
	v_add_u32_e32 v0, s8, v208
	v_add_u32_e32 v12, s9, v208
	ds_read_b128 v[16:19], v0
	ds_read_b128 v[20:23], v0 offset:1024
	ds_read_b128 v[24:27], v0 offset:2048
	ds_read_b128 v[28:31], v0 offset:3072
	ds_read_b128 v[0:3], v12
	ds_read_b128 v[4:7], v12 offset:1024
	ds_read_b128 v[8:11], v12 offset:2048
	ds_read_b128 v[12:15], v12 offset:3072
	v_lshl_add_u64 v[194:195], s[10:11], 0, v[168:169]
	s_add_i32 m0, s83, 0xc000
	ds_read_b128 v[172:175], v210
	ds_read_b128 v[176:179], v210 offset:1024
	ds_read_b128 v[228:231], v210 offset:2048
	ds_read_b128 v[232:235], v210 offset:3072
	ds_read_b128 v[236:239], v210 offset:4096
	ds_read_b128 v[240:243], v210 offset:5120
	ds_read_b128 v[186:189], v210 offset:6144
	ds_read_b128 v[190:193], v210 offset:7168
	global_load_lds_dwordx4 v[194:195], off
	v_lshl_add_u64 v[194:195], s[10:11], 0, v[170:171]
	s_add_i32 m0, s83, 0xe000
	s_nop 0
	global_load_lds_dwordx4 v[194:195], off
	s_waitcnt vmcnt(8)
	s_waitcnt lgkmcnt(0)
	s_barrier
	s_waitcnt lgkmcnt(0)
	v_mfma_f32_16x16x128_f8f6f4 v[158:161], v[16:23], v[172:179], v[158:161]
	v_mfma_f32_16x16x128_f8f6f4 v[154:157], v[24:31], v[172:179], v[154:157]
	v_mfma_f32_16x16x128_f8f6f4 v[142:145], v[16:23], v[228:235], v[142:145]
	v_mfma_f32_16x16x128_f8f6f4 v[138:141], v[24:31], v[228:235], v[138:141]
	v_mfma_f32_16x16x128_f8f6f4 v[126:129], v[16:23], v[236:243], v[126:129]
	v_mfma_f32_16x16x128_f8f6f4 v[122:125], v[24:31], v[236:243], v[122:125]
	v_mfma_f32_16x16x128_f8f6f4 v[110:113], v[16:23], v[186:193], v[110:113]
	v_mfma_f32_16x16x128_f8f6f4 v[106:109], v[24:31], v[186:193], v[106:109]
	v_mfma_f32_16x16x128_f8f6f4 v[150:153], v[0:7], v[172:179], v[150:153]
	v_mfma_f32_16x16x128_f8f6f4 v[146:149], v[8:15], v[172:179], v[146:149]
	v_mfma_f32_16x16x128_f8f6f4 v[134:137], v[0:7], v[228:235], v[134:137]
	v_mfma_f32_16x16x128_f8f6f4 v[130:133], v[8:15], v[228:235], v[130:133]
	v_mfma_f32_16x16x128_f8f6f4 v[118:121], v[0:7], v[236:243], v[118:121]
	v_mfma_f32_16x16x128_f8f6f4 v[114:117], v[8:15], v[236:243], v[114:117]
	v_mfma_f32_16x16x128_f8f6f4 v[102:105], v[0:7], v[186:193], v[102:105]
	v_mfma_f32_16x16x128_f8f6f4 v[98:101], v[8:15], v[186:193], v[98:101]
	s_barrier
	s_add_i32 s8, s8, s77
	v_lshl_add_u64 v[172:173], s[72:73], 0, v[32:33]
	s_mov_b32 m0, s8
	ds_read_b128 v[186:189], v210 offset:16384
	ds_read_b128 v[190:193], v210 offset:17408
	ds_read_b128 v[228:231], v210 offset:18432
	ds_read_b128 v[232:235], v210 offset:19456
	ds_read_b128 v[236:239], v210 offset:20480
	ds_read_b128 v[240:243], v210 offset:21504
	ds_read_b128 v[194:197], v210 offset:22528
	ds_read_b128 v[198:201], v210 offset:23552
	global_load_lds_dwordx4 v[172:173], off
	s_add_i32 m0, s8, 0x2000
	s_add_u32 s96, s72, 0x20000
	v_lshl_add_u64 v[174:175], s[72:73], 0, v[166:167]
	s_addc_u32 s97, s73, 0
	s_add_i32 s8, s9, s77
	global_load_lds_dwordx4 v[174:175], off
	v_lshl_add_u64 v[176:177], s[96:97], 0, v[32:33]
	s_mov_b32 m0, s8
	v_lshl_add_u64 v[178:179], s[74:75], 0, v[164:165]
	global_load_lds_dwordx4 v[176:177], off
	v_lshl_add_u64 v[176:177], s[96:97], 0, v[166:167]
	s_add_i32 m0, s8, 0x2000
	s_nop 0
	global_load_lds_dwordx4 v[176:177], off
	v_lshl_add_u64 v[176:177], s[74:75], 0, v[162:163]
	s_mov_b32 m0, s83
	s_nop 0
	global_load_lds_dwordx4 v[176:177], off
	s_mov_b32 m0, s16
	s_nop 0
	global_load_lds_dwordx4 v[178:179], off
	s_waitcnt vmcnt(8)
	s_waitcnt lgkmcnt(0)
	s_barrier
	s_waitcnt lgkmcnt(0)
	v_mfma_f32_16x16x128_f8f6f4 v[94:97], v[16:23], v[186:193], v[94:97]
	v_mfma_f32_16x16x128_f8f6f4 v[90:93], v[24:31], v[186:193], v[90:93]
	v_mfma_f32_16x16x128_f8f6f4 v[78:81], v[16:23], v[228:235], v[78:81]
	v_mfma_f32_16x16x128_f8f6f4 v[74:77], v[24:31], v[228:235], v[74:77]
	v_mfma_f32_16x16x128_f8f6f4 v[62:65], v[16:23], v[236:243], v[62:65]
	v_mfma_f32_16x16x128_f8f6f4 v[58:61], v[24:31], v[236:243], v[58:61]
	v_mfma_f32_16x16x128_f8f6f4 v[46:49], v[16:23], v[194:201], v[46:49]
	v_mfma_f32_16x16x128_f8f6f4 v[42:45], v[24:31], v[194:201], v[42:45]
	v_mfma_f32_16x16x128_f8f6f4 v[86:89], v[0:7], v[186:193], v[86:89]
	v_mfma_f32_16x16x128_f8f6f4 v[82:85], v[8:15], v[186:193], v[82:85]
	v_mfma_f32_16x16x128_f8f6f4 v[70:73], v[0:7], v[228:235], v[70:73]
	v_mfma_f32_16x16x128_f8f6f4 v[66:69], v[8:15], v[228:235], v[66:69]
	v_mfma_f32_16x16x128_f8f6f4 v[54:57], v[0:7], v[236:243], v[54:57]
	v_mfma_f32_16x16x128_f8f6f4 v[50:53], v[8:15], v[236:243], v[50:53]
	v_mfma_f32_16x16x128_f8f6f4 v[38:41], v[0:7], v[194:201], v[38:41]
	v_mfma_f32_16x16x128_f8f6f4 v[34:37], v[8:15], v[194:201], v[34:37]
	s_barrier
	s_add_i32 s56, 0, 0x18000
	s_add_i32 s57, 0, 0x1c000
	v_add_u32_e32 v12, s56, v208
	v_add_u32_e32 v28, s57, v208
	ds_read_b128 v[0:3], v12
	ds_read_b128 v[4:7], v12 offset:1024
	ds_read_b128 v[8:11], v12 offset:2048
	ds_read_b128 v[12:15], v12 offset:3072
	ds_read_b128 v[16:19], v28
	ds_read_b128 v[20:23], v28 offset:1024
	ds_read_b128 v[24:27], v28 offset:2048
	ds_read_b128 v[28:31], v28 offset:3072
	s_add_u32 s8, s74, 0x20000
	s_addc_u32 s9, s75, 0
	s_mov_b32 m0, s17
	v_lshl_add_u64 v[244:245], s[8:9], 0, v[162:163]
	ds_read_b128 v[186:189], v210 offset:32768
	ds_read_b128 v[190:193], v210 offset:33792
	ds_read_b128 v[194:197], v210 offset:34816
	ds_read_b128 v[198:201], v210 offset:35840
	ds_read_b128 v[228:231], v210 offset:36864
	ds_read_b128 v[232:235], v210 offset:37888
	ds_read_b128 v[236:239], v210 offset:38912
	ds_read_b128 v[240:243], v210 offset:39936
	global_load_lds_dwordx4 v[244:245], off
	v_lshl_add_u64 v[244:245], s[8:9], 0, v[164:165]
	s_mov_b32 m0, s84
	s_nop 0
	global_load_lds_dwordx4 v[244:245], off
	s_waitcnt vmcnt(8)
	s_waitcnt lgkmcnt(0)
	s_barrier
	s_waitcnt lgkmcnt(0)
	v_mfma_f32_16x16x128_f8f6f4 v[158:161], v[0:7], v[186:193], v[158:161]
	v_mfma_f32_16x16x128_f8f6f4 v[154:157], v[8:15], v[186:193], v[154:157]
	v_mfma_f32_16x16x128_f8f6f4 v[142:145], v[0:7], v[194:201], v[142:145]
	v_mfma_f32_16x16x128_f8f6f4 v[138:141], v[8:15], v[194:201], v[138:141]
	v_mfma_f32_16x16x128_f8f6f4 v[126:129], v[0:7], v[228:235], v[126:129]
	v_mfma_f32_16x16x128_f8f6f4 v[122:125], v[8:15], v[228:235], v[122:125]
	v_mfma_f32_16x16x128_f8f6f4 v[110:113], v[0:7], v[236:243], v[110:113]
	v_mfma_f32_16x16x128_f8f6f4 v[106:109], v[8:15], v[236:243], v[106:109]
	v_mfma_f32_16x16x128_f8f6f4 v[150:153], v[16:23], v[186:193], v[150:153]
	v_mfma_f32_16x16x128_f8f6f4 v[146:149], v[24:31], v[186:193], v[146:149]
	v_mfma_f32_16x16x128_f8f6f4 v[134:137], v[16:23], v[194:201], v[134:137]
	v_mfma_f32_16x16x128_f8f6f4 v[130:133], v[24:31], v[194:201], v[130:133]
	v_mfma_f32_16x16x128_f8f6f4 v[118:121], v[16:23], v[228:235], v[118:121]
	v_mfma_f32_16x16x128_f8f6f4 v[114:117], v[24:31], v[228:235], v[114:117]
	v_mfma_f32_16x16x128_f8f6f4 v[102:105], v[16:23], v[236:243], v[102:105]
	v_mfma_f32_16x16x128_f8f6f4 v[98:101], v[24:31], v[236:243], v[98:101]
	s_barrier
	s_add_i32 s8, s56, s77
	v_lshl_add_u64 v[172:173], v[172:173], 0, s[38:39]
	s_mov_b32 m0, s8
	ds_read_b128 v[186:189], v210 offset:49152
	ds_read_b128 v[190:193], v210 offset:50176
	ds_read_b128 v[194:197], v210 offset:51200
	ds_read_b128 v[198:201], v210 offset:52224
	ds_read_b128 v[228:231], v210 offset:53248
	ds_read_b128 v[232:235], v210 offset:54272
	ds_read_b128 v[236:239], v210 offset:55296
	ds_read_b128 v[240:243], v210 offset:56320
	global_load_lds_dwordx4 v[172:173], off
	s_add_i32 m0, s8, 0x2000
	s_add_u32 s8, s72, 0x20080
	v_lshl_add_u64 v[172:173], v[174:175], 0, s[38:39]
	s_addc_u32 s9, s73, 0
	s_add_i32 s56, s57, s77
	global_load_lds_dwordx4 v[172:173], off
	v_lshl_add_u64 v[172:173], s[8:9], 0, v[32:33]
	s_mov_b32 m0, s56
	s_nop 0
	global_load_lds_dwordx4 v[172:173], off
	v_lshl_add_u64 v[172:173], s[8:9], 0, v[166:167]
	s_add_i32 m0, s56, 0x2000
	s_nop 0
	global_load_lds_dwordx4 v[172:173], off
	v_lshl_add_u64 v[172:173], v[176:177], 0, s[38:39]
	s_mov_b32 m0, s85
	s_nop 0
	global_load_lds_dwordx4 v[172:173], off
	v_lshl_add_u64 v[172:173], v[178:179], 0, s[38:39]
	s_mov_b32 m0, s86
	s_nop 0
	global_load_lds_dwordx4 v[172:173], off
	s_waitcnt vmcnt(8)
	s_waitcnt lgkmcnt(0)
	s_barrier
	s_waitcnt lgkmcnt(0)
	v_mfma_f32_16x16x128_f8f6f4 v[94:97], v[0:7], v[186:193], v[94:97]
	v_mfma_f32_16x16x128_f8f6f4 v[90:93], v[8:15], v[186:193], v[90:93]
	v_mfma_f32_16x16x128_f8f6f4 v[78:81], v[0:7], v[194:201], v[78:81]
	v_mfma_f32_16x16x128_f8f6f4 v[74:77], v[8:15], v[194:201], v[74:77]
	v_mfma_f32_16x16x128_f8f6f4 v[62:65], v[0:7], v[228:235], v[62:65]
	v_mfma_f32_16x16x128_f8f6f4 v[58:61], v[8:15], v[228:235], v[58:61]
	v_mfma_f32_16x16x128_f8f6f4 v[46:49], v[0:7], v[236:243], v[46:49]
	v_mfma_f32_16x16x128_f8f6f4 v[42:45], v[8:15], v[236:243], v[42:45]
	v_mfma_f32_16x16x128_f8f6f4 v[86:89], v[16:23], v[186:193], v[86:89]
	v_mfma_f32_16x16x128_f8f6f4 v[82:85], v[24:31], v[186:193], v[82:85]
	v_mfma_f32_16x16x128_f8f6f4 v[70:73], v[16:23], v[194:201], v[70:73]
	v_mfma_f32_16x16x128_f8f6f4 v[66:69], v[24:31], v[194:201], v[66:69]
	v_mfma_f32_16x16x128_f8f6f4 v[54:57], v[16:23], v[228:235], v[54:57]
	v_mfma_f32_16x16x128_f8f6f4 v[50:53], v[24:31], v[228:235], v[50:53]
	v_mfma_f32_16x16x128_f8f6f4 v[38:41], v[16:23], v[236:243], v[38:41]
	v_mfma_f32_16x16x128_f8f6f4 v[34:37], v[24:31], v[236:243], v[34:37]
	s_barrier
	s_add_i32 s94, s94, 2
	s_add_u32 s10, s10, 0x100
	s_addc_u32 s11, s11, 0
	s_add_u32 s92, s92, 0x100
	s_addc_u32 s93, s93, 0
	s_cmp_gt_u32 s94, 5
	s_cbranch_scc0 .LBB0_212
	s_and_b64 vcc, exec, s[20:21]
	s_cbranch_vccz .LBB0_215
	s_barrier

.LBB0_485:
	v_readlane_b32 s16, v254, 30
	v_mov_b32_e32 v163, v33
	v_readlane_b32 s17, v254, 31
	v_mov_b32_e32 v165, v33
	s_lshl_b32 s2, s14, 5
	v_lshl_add_u64 v[90:91], s[16:17], 0, v[162:163]
	v_lshl_add_u64 v[92:93], s[16:17], 0, v[164:165]
	s_add_i32 s17, 0, 0x18000
	s_and_b32 s45, s2, 0x60
	s_add_i32 s2, s17, s9
	s_lshl_b32 s16, s44, 13
	v_lshl_add_u64 v[68:69], v[78:79], 0, s[38:39]
	s_mov_b32 m0, s2
	s_add_i32 s73, s2, 0x2000
	s_add_i32 s67, s77, 0x8000
	s_add_i32 s74, s77, 0xa000
	s_waitcnt vmcnt(2)
	s_barrier
	global_load_lds_dwordx4 v[68:69], off
	v_lshl_add_u64 v[70:71], v[80:81], 0, s[38:39]
	s_mov_b32 m0, s73
	s_add_u32 s14, s10, 0x20080
	global_load_lds_dwordx4 v[70:71], off
	v_lshl_add_u64 v[66:67], v[90:91], 0, s[38:39]
	s_mov_b32 m0, s67
	s_addc_u32 s15, s11, 0
	s_add_i32 s18, 0, 0x1c000
	global_load_lds_dwordx4 v[66:67], off
	v_lshl_add_u64 v[72:73], v[92:93], 0, s[38:39]
	s_mov_b32 m0, s74
	s_add_i32 s75, s18, s9
	global_load_lds_dwordx4 v[72:73], off
	v_lshl_add_u64 v[74:75], s[14:15], 0, v[32:33]
	s_mov_b32 m0, s75
	s_add_i32 s76, s75, 0x2000
	global_load_lds_dwordx4 v[74:75], off
	v_lshl_add_u64 v[76:77], s[14:15], 0, v[166:167]
	s_mov_b32 m0, s76
	v_lshlrev_b32_e32 v1, 2, v213
	global_load_lds_dwordx4 v[76:77], off
	v_lshl_or_b32 v0, v213, 6, v214
	v_and_b32_e32 v1, 32, v1
	v_bitop3_b32 v0, v0, s16, v1 bitop3:0xde
	v_lshl_or_b32 v1, s45, 7, v215
	s_add_i32 s85, 0, 0x10000
	v_add_u32_e32 v98, s85, v1
	s_add_i32 s85, s85, s9
	s_add_i32 s87, 0, 0x14000
	s_add_i32 s89, s77, 0xc000
	s_add_i32 s88, s77, 0xe000
	s_add_i32 s84, s85, 0x2000
	s_add_u32 s34, s10, 0x20100
	v_add_u32_e32 v97, s87, v1
	s_addc_u32 s35, s11, 0
	s_add_i32 s87, s87, s9
	s_waitcnt vmcnt(6)
	s_barrier
	s_add_i32 s86, s87, 0x2000
	ds_read_b128 v[4:7], v98
	ds_read_b128 v[8:11], v98 offset:1024
	ds_read_b128 v[16:19], v98 offset:2048
	ds_read_b128 v[20:23], v98 offset:3072
	ds_read_b128 v[100:103], v97
	ds_read_b128 v[104:107], v97 offset:1024
	ds_read_b128 v[108:111], v97 offset:2048
	ds_read_b128 v[112:115], v97 offset:3072
	s_add_u32 s20, s10, 0x20180
	s_addc_u32 s21, s11, 0
	v_add_u32_e32 v95, s18, v1
	s_add_u32 s18, s10, 0x20200
	s_addc_u32 s19, s11, 0
	v_readlane_b32 s14, v254, 16
	s_add_u32 s16, s10, 0x20280
	v_readlane_b32 s15, v254, 17
	v_add_u32_e32 v96, s17, v1
	s_addc_u32 s17, s11, 0
	v_lshl_add_u64 v[86:87], s[14:15], 0, v[162:163]
	v_lshl_add_u64 v[88:89], s[14:15], 0, v[164:165]
	s_add_u32 s14, s10, 0x20300
	s_addc_u32 s15, s11, 0
	s_add_u32 s10, s10, 0x20380
	s_addc_u32 s11, s11, 0
	v_add_u32_e32 v94, 0, v0
	s_cmpk_gt_u32 s8, 0xff
	v_readlane_b32 s8, v254, 18
	v_readlane_b32 s9, v254, 19
	s_mov_b32 m0, s89
	ds_read_b128 v[34:37], v94
	ds_read_b128 v[38:41], v94 offset:1024
	ds_read_b128 v[116:119], v94 offset:2048
	ds_read_b128 v[120:123], v94 offset:3072
	ds_read_b128 v[124:127], v94 offset:4096
	ds_read_b128 v[128:131], v94 offset:5120
	ds_read_b128 v[132:135], v94 offset:6144
	ds_read_b128 v[136:139], v94 offset:7168
	v_lshl_add_u64 v[0:1], s[8:9], 0, v[162:163]
	global_load_lds_dwordx4 v[0:1], off
	v_lshl_add_u64 v[0:1], s[8:9], 0, v[164:165]
	s_mov_b32 m0, s88
	s_nop 0
	global_load_lds_dwordx4 v[0:1], off
	s_waitcnt vmcnt(8)
	s_waitcnt lgkmcnt(0)
	s_barrier
	s_mov_b32 s28, s29
	s_mov_b32 s30, s29
	s_mov_b32 s31, s29
	v_mov_b64_e32 v[64:65], s[30:31]
	v_mov_b64_e32 v[60:61], s[30:31]
	v_mov_b64_e32 v[48:49], s[30:31]
	v_mov_b64_e32 v[44:45], s[30:31]
	v_mov_b64_e32 v[28:29], s[28:29]
	v_mov_b64_e32 v[24:25], s[28:29]
	v_mov_b64_e32 v[12:13], s[28:29]
	v_mov_b64_e32 v[62:63], s[28:29]
	v_mov_b64_e32 v[58:59], s[28:29]
	v_mov_b64_e32 v[46:47], s[28:29]
	v_mov_b64_e32 v[42:43], s[28:29]
	v_mov_b64_e32 v[30:31], s[30:31]
	v_mov_b64_e32 v[26:27], s[30:31]
	v_mov_b64_e32 v[14:15], s[30:31]
	v_mov_b64_e32 v[0:1], s[28:29]
	s_waitcnt lgkmcnt(0)
	v_mfma_f32_16x16x128_f8f6f4 v[62:65], v[4:11], v[34:41], v[62:65]
	v_mfma_f32_16x16x128_f8f6f4 v[58:61], v[16:23], v[34:41], v[58:61]
	v_mfma_f32_16x16x128_f8f6f4 v[46:49], v[4:11], v[116:123], v[46:49]
	v_mfma_f32_16x16x128_f8f6f4 v[42:45], v[16:23], v[116:123], v[42:45]
	v_mfma_f32_16x16x128_f8f6f4 v[28:31], v[4:11], v[124:131], v[28:31]
	v_mfma_f32_16x16x128_f8f6f4 v[24:27], v[16:23], v[124:131], v[24:27]
	v_mfma_f32_16x16x128_f8f6f4 v[12:15], v[4:11], v[132:139], v[12:15]
	v_mov_b64_e32 v[8:9], s[28:29]
	v_mov_b64_e32 v[2:3], s[30:31]
	v_mov_b64_e32 v[10:11], s[30:31]
	v_mfma_f32_16x16x128_f8f6f4 v[8:11], v[16:23], v[132:139], v[8:11]
	v_mov_b64_e32 v[56:57], s[30:31]
	v_mov_b64_e32 v[52:53], s[30:31]
	v_mov_b64_e32 v[54:55], s[28:29]
	v_mov_b64_e32 v[50:51], s[28:29]
	v_mfma_f32_16x16x128_f8f6f4 v[54:57], v[100:107], v[34:41], v[54:57]
	v_mfma_f32_16x16x128_f8f6f4 v[50:53], v[108:115], v[34:41], v[50:53]
	v_mov_b64_e32 v[40:41], s[30:31]
	v_mov_b64_e32 v[36:37], s[30:31]
	v_mov_b64_e32 v[20:21], s[28:29]
	v_mov_b64_e32 v[16:17], s[28:29]
	v_mov_b64_e32 v[4:5], s[28:29]
	v_mov_b64_e32 v[38:39], s[28:29]
	v_mov_b64_e32 v[34:35], s[28:29]
	v_mov_b64_e32 v[22:23], s[30:31]
	v_mov_b64_e32 v[18:19], s[30:31]
	v_mov_b64_e32 v[6:7], s[30:31]
	v_mfma_f32_16x16x128_f8f6f4 v[38:41], v[100:107], v[116:123], v[38:41]
	v_mfma_f32_16x16x128_f8f6f4 v[34:37], v[108:115], v[116:123], v[34:37]
	v_mfma_f32_16x16x128_f8f6f4 v[20:23], v[100:107], v[124:131], v[20:23]
	v_mfma_f32_16x16x128_f8f6f4 v[16:19], v[108:115], v[124:131], v[16:19]
	v_mfma_f32_16x16x128_f8f6f4 v[4:7], v[100:107], v[132:139], v[4:7]
	v_mfma_f32_16x16x128_f8f6f4 v[0:3], v[108:115], v[132:139], v[0:3]
	s_barrier
	s_mov_b64 s[8:9], 0x100
	s_mov_b32 m0, s85
	v_lshl_add_u64 v[100:101], v[78:79], 0, s[8:9]
	global_load_lds_dwordx4 v[100:101], off
	v_lshl_add_u64 v[100:101], v[80:81], 0, s[8:9]
	s_mov_b32 m0, s84
	s_nop 0
	global_load_lds_dwordx4 v[100:101], off
	v_lshl_add_u64 v[100:101], s[34:35], 0, v[32:33]
	s_mov_b32 m0, s87
	s_nop 0
	global_load_lds_dwordx4 v[100:101], off
	v_lshl_add_u64 v[100:101], s[34:35], 0, v[166:167]
	s_mov_b32 m0, s86
	s_nop 0
	global_load_lds_dwordx4 v[100:101], off
	v_lshl_add_u64 v[100:101], v[90:91], 0, s[8:9]
	s_mov_b32 m0, s77
	s_nop 0
	global_load_lds_dwordx4 v[100:101], off
	v_lshl_add_u64 v[100:101], v[92:93], 0, s[8:9]
	s_mov_b32 m0, s83
	s_nop 0
	global_load_lds_dwordx4 v[100:101], off
	s_waitcnt vmcnt(8)
	s_waitcnt lgkmcnt(0)
	s_barrier
	s_barrier
	ds_read_b128 v[100:103], v96
	ds_read_b128 v[104:107], v96 offset:1024
	ds_read_b128 v[108:111], v96 offset:2048
	ds_read_b128 v[112:115], v96 offset:3072
	ds_read_b128 v[116:119], v95
	ds_read_b128 v[120:123], v95 offset:1024
	ds_read_b128 v[124:127], v95 offset:2048
	ds_read_b128 v[128:131], v95 offset:3072
	v_readlane_b32 s8, v254, 20
	v_readlane_b32 s9, v254, 21
	s_mov_b32 m0, s66
	ds_read_b128 v[132:135], v94 offset:32768
	ds_read_b128 v[136:139], v94 offset:33792
	ds_read_b128 v[140:143], v94 offset:34816
	ds_read_b128 v[144:147], v94 offset:35840
	ds_read_b128 v[148:151], v94 offset:36864
	ds_read_b128 v[152:155], v94 offset:37888
	ds_read_b128 v[168:171], v94 offset:38912
	ds_read_b128 v[172:175], v94 offset:39936
	v_lshl_add_u64 v[156:157], s[8:9], 0, v[162:163]
	global_load_lds_dwordx4 v[156:157], off
	v_lshl_add_u64 v[156:157], s[8:9], 0, v[164:165]
	s_mov_b32 m0, s72
	s_nop 0
	global_load_lds_dwordx4 v[156:157], off
	s_waitcnt vmcnt(8)
	s_waitcnt lgkmcnt(0)
	s_barrier
	s_waitcnt lgkmcnt(0)
	v_mfma_f32_16x16x128_f8f6f4 v[62:65], v[100:107], v[132:139], v[62:65]
	v_mfma_f32_16x16x128_f8f6f4 v[58:61], v[108:115], v[132:139], v[58:61]
	v_mfma_f32_16x16x128_f8f6f4 v[46:49], v[100:107], v[140:147], v[46:49]
	v_mfma_f32_16x16x128_f8f6f4 v[42:45], v[108:115], v[140:147], v[42:45]
	v_mfma_f32_16x16x128_f8f6f4 v[28:31], v[100:107], v[148:155], v[28:31]
	v_mfma_f32_16x16x128_f8f6f4 v[24:27], v[108:115], v[148:155], v[24:27]
	v_mfma_f32_16x16x128_f8f6f4 v[12:15], v[100:107], v[168:175], v[12:15]
	v_mfma_f32_16x16x128_f8f6f4 v[8:11], v[108:115], v[168:175], v[8:11]
	v_mfma_f32_16x16x128_f8f6f4 v[54:57], v[116:123], v[132:139], v[54:57]
	v_mfma_f32_16x16x128_f8f6f4 v[50:53], v[124:131], v[132:139], v[50:53]
	v_mfma_f32_16x16x128_f8f6f4 v[38:41], v[116:123], v[140:147], v[38:41]
	v_mfma_f32_16x16x128_f8f6f4 v[34:37], v[124:131], v[140:147], v[34:37]
	v_mfma_f32_16x16x128_f8f6f4 v[20:23], v[116:123], v[148:155], v[20:23]
	v_mfma_f32_16x16x128_f8f6f4 v[16:19], v[124:131], v[148:155], v[16:19]
	v_mfma_f32_16x16x128_f8f6f4 v[4:7], v[116:123], v[168:175], v[4:7]
	v_mfma_f32_16x16x128_f8f6f4 v[0:3], v[124:131], v[168:175], v[0:3]
	s_barrier
	s_mov_b64 s[8:9], 0x180
	s_mov_b32 m0, s2
	v_lshl_add_u64 v[100:101], v[78:79], 0, s[8:9]
	global_load_lds_dwordx4 v[100:101], off
	v_lshl_add_u64 v[100:101], v[80:81], 0, s[8:9]
	s_mov_b32 m0, s73
	s_nop 0
	global_load_lds_dwordx4 v[100:101], off
	v_lshl_add_u64 v[100:101], s[20:21], 0, v[32:33]
	s_mov_b32 m0, s75
	s_nop 0
	global_load_lds_dwordx4 v[100:101], off
	v_lshl_add_u64 v[100:101], s[20:21], 0, v[166:167]
	s_mov_b32 m0, s76
	s_nop 0
	global_load_lds_dwordx4 v[100:101], off
	v_lshl_add_u64 v[100:101], v[90:91], 0, s[8:9]
	s_mov_b32 m0, s67
	s_nop 0
	global_load_lds_dwordx4 v[100:101], off
	v_lshl_add_u64 v[100:101], v[92:93], 0, s[8:9]
	s_mov_b32 m0, s74
	s_nop 0
	global_load_lds_dwordx4 v[100:101], off
	s_waitcnt vmcnt(8)
	s_waitcnt lgkmcnt(0)
	s_barrier
	s_barrier
	ds_read_b128 v[100:103], v98
	ds_read_b128 v[104:107], v98 offset:1024
	ds_read_b128 v[108:111], v98 offset:2048
	ds_read_b128 v[112:115], v98 offset:3072
	ds_read_b128 v[116:119], v97
	ds_read_b128 v[120:123], v97 offset:1024
	ds_read_b128 v[124:127], v97 offset:2048
	ds_read_b128 v[128:131], v97 offset:3072
	v_readlane_b32 s8, v254, 22
	v_readlane_b32 s9, v254, 23
	s_mov_b32 m0, s89
	ds_read_b128 v[132:135], v94
	ds_read_b128 v[136:139], v94 offset:1024
	ds_read_b128 v[140:143], v94 offset:2048
	ds_read_b128 v[144:147], v94 offset:3072
	ds_read_b128 v[148:151], v94 offset:4096
	ds_read_b128 v[152:155], v94 offset:5120
	ds_read_b128 v[168:171], v94 offset:6144
	ds_read_b128 v[172:175], v94 offset:7168
	v_lshl_add_u64 v[156:157], s[8:9], 0, v[162:163]
	global_load_lds_dwordx4 v[156:157], off
	v_lshl_add_u64 v[156:157], s[8:9], 0, v[164:165]
	s_mov_b32 m0, s88
	s_nop 0
	global_load_lds_dwordx4 v[156:157], off
	s_waitcnt vmcnt(8)
	s_waitcnt lgkmcnt(0)
	s_barrier
	s_waitcnt lgkmcnt(0)
	v_mfma_f32_16x16x128_f8f6f4 v[62:65], v[100:107], v[132:139], v[62:65]
	v_mfma_f32_16x16x128_f8f6f4 v[58:61], v[108:115], v[132:139], v[58:61]
	v_mfma_f32_16x16x128_f8f6f4 v[46:49], v[100:107], v[140:147], v[46:49]
	v_mfma_f32_16x16x128_f8f6f4 v[42:45], v[108:115], v[140:147], v[42:45]
	v_mfma_f32_16x16x128_f8f6f4 v[28:31], v[100:107], v[148:155], v[28:31]
	v_mfma_f32_16x16x128_f8f6f4 v[24:27], v[108:115], v[148:155], v[24:27]
	v_mfma_f32_16x16x128_f8f6f4 v[12:15], v[100:107], v[168:175], v[12:15]
	v_mfma_f32_16x16x128_f8f6f4 v[8:11], v[108:115], v[168:175], v[8:11]
	v_mfma_f32_16x16x128_f8f6f4 v[54:57], v[116:123], v[132:139], v[54:57]
	v_mfma_f32_16x16x128_f8f6f4 v[50:53], v[124:131], v[132:139], v[50:53]
	v_mfma_f32_16x16x128_f8f6f4 v[38:41], v[116:123], v[140:147], v[38:41]
	v_mfma_f32_16x16x128_f8f6f4 v[34:37], v[124:131], v[140:147], v[34:37]
	v_mfma_f32_16x16x128_f8f6f4 v[20:23], v[116:123], v[148:155], v[20:23]
	v_mfma_f32_16x16x128_f8f6f4 v[16:19], v[124:131], v[148:155], v[16:19]
	v_mfma_f32_16x16x128_f8f6f4 v[4:7], v[116:123], v[168:175], v[4:7]
	v_mfma_f32_16x16x128_f8f6f4 v[0:3], v[124:131], v[168:175], v[0:3]
	s_barrier
	s_mov_b64 s[8:9], 0x200
	s_mov_b32 m0, s85
	v_lshl_add_u64 v[100:101], v[78:79], 0, s[8:9]
	global_load_lds_dwordx4 v[100:101], off
	v_lshl_add_u64 v[100:101], v[80:81], 0, s[8:9]
	s_mov_b32 m0, s84
	s_nop 0
	global_load_lds_dwordx4 v[100:101], off
	v_lshl_add_u64 v[100:101], s[18:19], 0, v[32:33]
	s_mov_b32 m0, s87
	s_nop 0
	global_load_lds_dwordx4 v[100:101], off
	v_lshl_add_u64 v[100:101], s[18:19], 0, v[166:167]
	s_mov_b32 m0, s86
	s_nop 0
	global_load_lds_dwordx4 v[100:101], off
	v_lshl_add_u64 v[100:101], v[90:91], 0, s[8:9]
	s_mov_b32 m0, s77
	s_nop 0
	global_load_lds_dwordx4 v[100:101], off
	v_lshl_add_u64 v[100:101], v[92:93], 0, s[8:9]
	s_mov_b32 m0, s83
	s_nop 0
	global_load_lds_dwordx4 v[100:101], off
	s_waitcnt vmcnt(8)
	s_waitcnt lgkmcnt(0)
	s_barrier
	s_barrier
	ds_read_b128 v[100:103], v96
	ds_read_b128 v[104:107], v96 offset:1024
	ds_read_b128 v[108:111], v96 offset:2048
	ds_read_b128 v[112:115], v96 offset:3072
	ds_read_b128 v[116:119], v95
	ds_read_b128 v[120:123], v95 offset:1024
	ds_read_b128 v[124:127], v95 offset:2048
	ds_read_b128 v[128:131], v95 offset:3072
	v_readlane_b32 s8, v254, 24
	v_readlane_b32 s9, v254, 25
	s_mov_b32 m0, s66
	ds_read_b128 v[132:135], v94 offset:32768
	ds_read_b128 v[136:139], v94 offset:33792
	ds_read_b128 v[140:143], v94 offset:34816
	ds_read_b128 v[144:147], v94 offset:35840
	ds_read_b128 v[148:151], v94 offset:36864
	ds_read_b128 v[152:155], v94 offset:37888
	ds_read_b128 v[168:171], v94 offset:38912
	ds_read_b128 v[172:175], v94 offset:39936
	v_lshl_add_u64 v[156:157], s[8:9], 0, v[162:163]
	global_load_lds_dwordx4 v[156:157], off
	v_lshl_add_u64 v[156:157], s[8:9], 0, v[164:165]
	s_mov_b32 m0, s72
	s_nop 0
	global_load_lds_dwordx4 v[156:157], off
	s_waitcnt vmcnt(8)
	s_waitcnt lgkmcnt(0)
	s_barrier
	s_waitcnt lgkmcnt(0)
	v_mfma_f32_16x16x128_f8f6f4 v[62:65], v[100:107], v[132:139], v[62:65]
	v_mfma_f32_16x16x128_f8f6f4 v[58:61], v[108:115], v[132:139], v[58:61]
	v_mfma_f32_16x16x128_f8f6f4 v[46:49], v[100:107], v[140:147], v[46:49]
	v_mfma_f32_16x16x128_f8f6f4 v[42:45], v[108:115], v[140:147], v[42:45]
	v_mfma_f32_16x16x128_f8f6f4 v[28:31], v[100:107], v[148:155], v[28:31]
	v_mfma_f32_16x16x128_f8f6f4 v[24:27], v[108:115], v[148:155], v[24:27]
	v_mfma_f32_16x16x128_f8f6f4 v[12:15], v[100:107], v[168:175], v[12:15]
	v_mfma_f32_16x16x128_f8f6f4 v[8:11], v[108:115], v[168:175], v[8:11]
	v_mfma_f32_16x16x128_f8f6f4 v[54:57], v[116:123], v[132:139], v[54:57]
	v_mfma_f32_16x16x128_f8f6f4 v[50:53], v[124:131], v[132:139], v[50:53]
	v_mfma_f32_16x16x128_f8f6f4 v[38:41], v[116:123], v[140:147], v[38:41]
	v_mfma_f32_16x16x128_f8f6f4 v[34:37], v[124:131], v[140:147], v[34:37]
	v_mfma_f32_16x16x128_f8f6f4 v[20:23], v[116:123], v[148:155], v[20:23]
	v_mfma_f32_16x16x128_f8f6f4 v[16:19], v[124:131], v[148:155], v[16:19]
	v_mfma_f32_16x16x128_f8f6f4 v[4:7], v[116:123], v[168:175], v[4:7]
	v_mfma_f32_16x16x128_f8f6f4 v[0:3], v[124:131], v[168:175], v[0:3]
	s_barrier
	s_mov_b64 s[8:9], 0x280
	s_mov_b32 m0, s2
	v_lshl_add_u64 v[100:101], v[78:79], 0, s[8:9]
	global_load_lds_dwordx4 v[100:101], off
	v_lshl_add_u64 v[100:101], v[80:81], 0, s[8:9]
	s_mov_b32 m0, s73
	s_nop 0
	global_load_lds_dwordx4 v[100:101], off
	v_lshl_add_u64 v[100:101], s[16:17], 0, v[32:33]
	s_mov_b32 m0, s75
	s_nop 0
	global_load_lds_dwordx4 v[100:101], off
	v_lshl_add_u64 v[100:101], s[16:17], 0, v[166:167]
	s_mov_b32 m0, s76
	s_nop 0
	global_load_lds_dwordx4 v[100:101], off
	v_lshl_add_u64 v[100:101], v[90:91], 0, s[8:9]
	s_mov_b32 m0, s67
	s_nop 0
	global_load_lds_dwordx4 v[100:101], off
	v_lshl_add_u64 v[100:101], v[92:93], 0, s[8:9]
	s_mov_b32 m0, s74
	s_nop 0
	global_load_lds_dwordx4 v[100:101], off
	s_waitcnt vmcnt(8)
	s_waitcnt lgkmcnt(0)
	s_barrier
	s_barrier
	ds_read_b128 v[100:103], v98
	ds_read_b128 v[104:107], v98 offset:1024
	ds_read_b128 v[108:111], v98 offset:2048
	ds_read_b128 v[112:115], v98 offset:3072
	ds_read_b128 v[116:119], v97
	ds_read_b128 v[120:123], v97 offset:1024
	ds_read_b128 v[124:127], v97 offset:2048
	ds_read_b128 v[128:131], v97 offset:3072
	v_readlane_b32 s8, v254, 26
	v_readlane_b32 s9, v254, 27
	s_mov_b32 m0, s89
	ds_read_b128 v[132:135], v94
	ds_read_b128 v[136:139], v94 offset:1024
	ds_read_b128 v[140:143], v94 offset:2048
	ds_read_b128 v[144:147], v94 offset:3072
	ds_read_b128 v[148:151], v94 offset:4096
	ds_read_b128 v[152:155], v94 offset:5120
	ds_read_b128 v[168:171], v94 offset:6144
	ds_read_b128 v[172:175], v94 offset:7168
	v_lshl_add_u64 v[156:157], s[8:9], 0, v[162:163]
	global_load_lds_dwordx4 v[156:157], off
	v_lshl_add_u64 v[156:157], s[8:9], 0, v[164:165]
	s_mov_b32 m0, s88
	s_nop 0
	global_load_lds_dwordx4 v[156:157], off
	s_waitcnt vmcnt(8)
	s_waitcnt lgkmcnt(0)
	s_barrier
	s_waitcnt lgkmcnt(0)
	v_mfma_f32_16x16x128_f8f6f4 v[62:65], v[100:107], v[132:139], v[62:65]
	v_mfma_f32_16x16x128_f8f6f4 v[58:61], v[108:115], v[132:139], v[58:61]
	v_mfma_f32_16x16x128_f8f6f4 v[46:49], v[100:107], v[140:147], v[46:49]
	v_mfma_f32_16x16x128_f8f6f4 v[42:45], v[108:115], v[140:147], v[42:45]
	v_mfma_f32_16x16x128_f8f6f4 v[28:31], v[100:107], v[148:155], v[28:31]
	v_mfma_f32_16x16x128_f8f6f4 v[24:27], v[108:115], v[148:155], v[24:27]
	v_mfma_f32_16x16x128_f8f6f4 v[12:15], v[100:107], v[168:175], v[12:15]
	v_mfma_f32_16x16x128_f8f6f4 v[8:11], v[108:115], v[168:175], v[8:11]
	v_mfma_f32_16x16x128_f8f6f4 v[54:57], v[116:123], v[132:139], v[54:57]
	v_mfma_f32_16x16x128_f8f6f4 v[50:53], v[124:131], v[132:139], v[50:53]
	v_mfma_f32_16x16x128_f8f6f4 v[38:41], v[116:123], v[140:147], v[38:41]
	v_mfma_f32_16x16x128_f8f6f4 v[34:37], v[124:131], v[140:147], v[34:37]
	v_mfma_f32_16x16x128_f8f6f4 v[20:23], v[116:123], v[148:155], v[20:23]
	v_mfma_f32_16x16x128_f8f6f4 v[16:19], v[124:131], v[148:155], v[16:19]
	v_mfma_f32_16x16x128_f8f6f4 v[4:7], v[116:123], v[168:175], v[4:7]
	v_mfma_f32_16x16x128_f8f6f4 v[0:3], v[124:131], v[168:175], v[0:3]
	s_barrier
	s_mov_b64 s[8:9], 0x300
	s_mov_b32 m0, s85
	v_lshl_add_u64 v[100:101], v[78:79], 0, s[8:9]
	global_load_lds_dwordx4 v[100:101], off
	v_lshl_add_u64 v[100:101], v[80:81], 0, s[8:9]
	s_mov_b32 m0, s84
	s_nop 0
	global_load_lds_dwordx4 v[100:101], off
	v_lshl_add_u64 v[100:101], s[14:15], 0, v[32:33]
	s_mov_b32 m0, s87
	s_nop 0
	global_load_lds_dwordx4 v[100:101], off
	v_lshl_add_u64 v[100:101], s[14:15], 0, v[166:167]
	s_mov_b32 m0, s86
	s_nop 0
	global_load_lds_dwordx4 v[100:101], off
	v_lshl_add_u64 v[100:101], v[90:91], 0, s[8:9]
	s_mov_b32 m0, s77
	s_nop 0
	global_load_lds_dwordx4 v[100:101], off
	v_lshl_add_u64 v[100:101], v[92:93], 0, s[8:9]
	s_mov_b32 m0, s83
	s_nop 0
	global_load_lds_dwordx4 v[100:101], off
	s_waitcnt vmcnt(8)
	s_waitcnt lgkmcnt(0)
	s_barrier
	s_barrier
	ds_read_b128 v[100:103], v96
	ds_read_b128 v[104:107], v96 offset:1024
	ds_read_b128 v[108:111], v96 offset:2048
	ds_read_b128 v[112:115], v96 offset:3072
	ds_read_b128 v[116:119], v95
	ds_read_b128 v[120:123], v95 offset:1024
	ds_read_b128 v[124:127], v95 offset:2048
	ds_read_b128 v[128:131], v95 offset:3072
	v_readlane_b32 s8, v254, 28
	v_readlane_b32 s9, v254, 29
	s_mov_b32 m0, s66
	ds_read_b128 v[132:135], v94 offset:32768
	ds_read_b128 v[136:139], v94 offset:33792
	ds_read_b128 v[140:143], v94 offset:34816
	ds_read_b128 v[144:147], v94 offset:35840
	ds_read_b128 v[148:151], v94 offset:36864
	ds_read_b128 v[152:155], v94 offset:37888
	ds_read_b128 v[168:171], v94 offset:38912
	ds_read_b128 v[172:175], v94 offset:39936
	v_lshl_add_u64 v[156:157], s[8:9], 0, v[162:163]
	global_load_lds_dwordx4 v[156:157], off
	v_lshl_add_u64 v[156:157], s[8:9], 0, v[164:165]
	s_mov_b32 m0, s72
	s_nop 0
	global_load_lds_dwordx4 v[156:157], off
	s_waitcnt vmcnt(8)
	s_waitcnt lgkmcnt(0)
	s_barrier
	s_waitcnt lgkmcnt(0)
	v_mfma_f32_16x16x128_f8f6f4 v[62:65], v[100:107], v[132:139], v[62:65]
	v_mfma_f32_16x16x128_f8f6f4 v[58:61], v[108:115], v[132:139], v[58:61]
	v_mfma_f32_16x16x128_f8f6f4 v[46:49], v[100:107], v[140:147], v[46:49]
	v_mfma_f32_16x16x128_f8f6f4 v[42:45], v[108:115], v[140:147], v[42:45]
	v_mfma_f32_16x16x128_f8f6f4 v[28:31], v[100:107], v[148:155], v[28:31]
	v_mfma_f32_16x16x128_f8f6f4 v[24:27], v[108:115], v[148:155], v[24:27]
	v_mfma_f32_16x16x128_f8f6f4 v[12:15], v[100:107], v[168:175], v[12:15]
	v_mfma_f32_16x16x128_f8f6f4 v[8:11], v[108:115], v[168:175], v[8:11]
	v_mfma_f32_16x16x128_f8f6f4 v[54:57], v[116:123], v[132:139], v[54:57]
	v_mfma_f32_16x16x128_f8f6f4 v[50:53], v[124:131], v[132:139], v[50:53]
	v_mfma_f32_16x16x128_f8f6f4 v[38:41], v[116:123], v[140:147], v[38:41]
	v_mfma_f32_16x16x128_f8f6f4 v[34:37], v[124:131], v[140:147], v[34:37]
	v_mfma_f32_16x16x128_f8f6f4 v[20:23], v[116:123], v[148:155], v[20:23]
	v_mfma_f32_16x16x128_f8f6f4 v[16:19], v[124:131], v[148:155], v[16:19]
	v_mfma_f32_16x16x128_f8f6f4 v[4:7], v[116:123], v[168:175], v[4:7]
	v_mfma_f32_16x16x128_f8f6f4 v[0:3], v[124:131], v[168:175], v[0:3]
	s_barrier
	s_mov_b64 s[8:9], 0x380
	s_mov_b32 m0, s2
	v_lshl_add_u64 v[100:101], v[78:79], 0, s[8:9]
	global_load_lds_dwordx4 v[100:101], off
	v_lshl_add_u64 v[100:101], v[80:81], 0, s[8:9]
	s_mov_b32 m0, s73
	s_nop 0
	global_load_lds_dwordx4 v[100:101], off
	v_lshl_add_u64 v[100:101], s[10:11], 0, v[32:33]
	s_mov_b32 m0, s75
	s_nop 0
	global_load_lds_dwordx4 v[100:101], off
	v_lshl_add_u64 v[100:101], s[10:11], 0, v[166:167]
	s_mov_b32 m0, s76
	s_nop 0
	global_load_lds_dwordx4 v[100:101], off
	v_lshl_add_u64 v[100:101], v[90:91], 0, s[8:9]
	s_mov_b32 m0, s67
	s_nop 0
	global_load_lds_dwordx4 v[100:101], off
	v_lshl_add_u64 v[100:101], v[92:93], 0, s[8:9]
	s_mov_b32 m0, s74
	s_nop 0
	global_load_lds_dwordx4 v[100:101], off
	s_waitcnt vmcnt(8)
	s_waitcnt lgkmcnt(0)
	s_barrier
	s_barrier
	ds_read_b128 v[100:103], v98
	ds_read_b128 v[104:107], v98 offset:1024
	ds_read_b128 v[108:111], v98 offset:2048
	ds_read_b128 v[112:115], v98 offset:3072
	ds_read_b128 v[116:119], v97
	ds_read_b128 v[120:123], v97 offset:1024
	ds_read_b128 v[124:127], v97 offset:2048
	ds_read_b128 v[128:131], v97 offset:3072
	v_readlane_b32 s8, v254, 32
	v_readlane_b32 s9, v254, 33
	s_mov_b32 m0, s89
	ds_read_b128 v[132:135], v94
	ds_read_b128 v[136:139], v94 offset:1024
	ds_read_b128 v[140:143], v94 offset:2048
	ds_read_b128 v[144:147], v94 offset:3072
	ds_read_b128 v[148:151], v94 offset:4096
	ds_read_b128 v[152:155], v94 offset:5120
	ds_read_b128 v[166:169], v94 offset:6144
	ds_read_b128 v[170:173], v94 offset:7168
	v_lshl_add_u64 v[98:99], s[8:9], 0, v[162:163]
	global_load_lds_dwordx4 v[98:99], off
	v_lshl_add_u64 v[98:99], s[8:9], 0, v[164:165]
	s_mov_b32 m0, s88
	s_nop 0
	global_load_lds_dwordx4 v[98:99], off
	s_waitcnt vmcnt(8)
	s_waitcnt lgkmcnt(0)
	s_barrier
	s_waitcnt lgkmcnt(0)
	v_mfma_f32_16x16x128_f8f6f4 v[62:65], v[100:107], v[132:139], v[62:65]
	v_mfma_f32_16x16x128_f8f6f4 v[58:61], v[108:115], v[132:139], v[58:61]
	v_mfma_f32_16x16x128_f8f6f4 v[46:49], v[100:107], v[140:147], v[46:49]
	v_mfma_f32_16x16x128_f8f6f4 v[42:45], v[108:115], v[140:147], v[42:45]
	v_mfma_f32_16x16x128_f8f6f4 v[28:31], v[100:107], v[148:155], v[28:31]
	v_mfma_f32_16x16x128_f8f6f4 v[24:27], v[108:115], v[148:155], v[24:27]
	v_mfma_f32_16x16x128_f8f6f4 v[12:15], v[100:107], v[166:173], v[12:15]
	v_mfma_f32_16x16x128_f8f6f4 v[8:11], v[108:115], v[166:173], v[8:11]
	v_mfma_f32_16x16x128_f8f6f4 v[54:57], v[116:123], v[132:139], v[54:57]
	v_mfma_f32_16x16x128_f8f6f4 v[50:53], v[124:131], v[132:139], v[50:53]
	v_mfma_f32_16x16x128_f8f6f4 v[38:41], v[116:123], v[140:147], v[38:41]
	v_mfma_f32_16x16x128_f8f6f4 v[34:37], v[124:131], v[140:147], v[34:37]
	v_mfma_f32_16x16x128_f8f6f4 v[20:23], v[116:123], v[148:155], v[20:23]
	v_mfma_f32_16x16x128_f8f6f4 v[16:19], v[124:131], v[148:155], v[16:19]
	v_mfma_f32_16x16x128_f8f6f4 v[4:7], v[116:123], v[166:173], v[4:7]
	v_mfma_f32_16x16x128_f8f6f4 v[0:3], v[124:131], v[166:173], v[0:3]
	s_barrier
	s_mov_b32 m0, s85
	s_nop 0
	global_load_lds_dwordx4 v[78:79], off
	s_mov_b32 m0, s84
	s_nop 0
	global_load_lds_dwordx4 v[80:81], off
	s_mov_b32 m0, s87
	s_nop 0
	global_load_lds_dwordx4 v[82:83], off
	s_mov_b32 m0, s86
	s_nop 0
	global_load_lds_dwordx4 v[84:85], off
	s_mov_b32 m0, s77
	s_nop 0
	global_load_lds_dwordx4 v[90:91], off
	s_mov_b32 m0, s83
	s_nop 0
	global_load_lds_dwordx4 v[92:93], off
	s_waitcnt vmcnt(8)
	s_waitcnt lgkmcnt(0)
	s_barrier
	s_barrier
	ds_read_b128 v[78:81], v96
	ds_read_b128 v[82:85], v96 offset:1024
	ds_read_b128 v[98:101], v96 offset:2048
	ds_read_b128 v[102:105], v96 offset:3072
	ds_read_b128 v[106:109], v95
	ds_read_b128 v[110:113], v95 offset:1024
	ds_read_b128 v[114:117], v95 offset:2048
	ds_read_b128 v[118:121], v95 offset:3072
	s_mov_b32 m0, s66
	ds_read_b128 v[122:125], v94 offset:32768
	ds_read_b128 v[126:129], v94 offset:33792
	ds_read_b128 v[130:133], v94 offset:34816
	ds_read_b128 v[134:137], v94 offset:35840
	ds_read_b128 v[138:141], v94 offset:36864
	ds_read_b128 v[142:145], v94 offset:37888
	ds_read_b128 v[90:93], v94 offset:38912
	ds_read_b128 v[94:97], v94 offset:39936
	global_load_lds_dwordx4 v[86:87], off
	s_mov_b32 m0, s72
	s_nop 0
	global_load_lds_dwordx4 v[88:89], off
	s_waitcnt vmcnt(8)
	s_waitcnt lgkmcnt(0)
	s_barrier
	s_waitcnt lgkmcnt(0)
	v_mfma_f32_16x16x128_f8f6f4 v[62:65], v[78:85], v[122:129], v[62:65]
	v_mfma_f32_16x16x128_f8f6f4 v[58:61], v[98:105], v[122:129], v[58:61]
	v_mfma_f32_16x16x128_f8f6f4 v[46:49], v[78:85], v[130:137], v[46:49]
	v_mfma_f32_16x16x128_f8f6f4 v[42:45], v[98:105], v[130:137], v[42:45]
	v_mfma_f32_16x16x128_f8f6f4 v[28:31], v[78:85], v[138:145], v[28:31]
	v_mfma_f32_16x16x128_f8f6f4 v[24:27], v[98:105], v[138:145], v[24:27]
	v_mfma_f32_16x16x128_f8f6f4 v[12:15], v[78:85], v[90:97], v[12:15]
	v_mfma_f32_16x16x128_f8f6f4 v[8:11], v[98:105], v[90:97], v[8:11]
	v_mfma_f32_16x16x128_f8f6f4 v[54:57], v[106:113], v[122:129], v[54:57]
	v_mfma_f32_16x16x128_f8f6f4 v[50:53], v[114:121], v[122:129], v[50:53]
	v_mfma_f32_16x16x128_f8f6f4 v[38:41], v[106:113], v[130:137], v[38:41]
	v_mfma_f32_16x16x128_f8f6f4 v[34:37], v[114:121], v[130:137], v[34:37]
	v_mfma_f32_16x16x128_f8f6f4 v[20:23], v[106:113], v[138:145], v[20:23]
	v_mfma_f32_16x16x128_f8f6f4 v[16:19], v[114:121], v[138:145], v[16:19]
	v_mfma_f32_16x16x128_f8f6f4 v[4:7], v[106:113], v[90:97], v[4:7]
	v_mfma_f32_16x16x128_f8f6f4 v[0:3], v[114:121], v[90:97], v[0:3]
	s_barrier
	s_mov_b32 m0, s2
	s_nop 0
	global_load_lds_dwordx4 v[68:69], off
	s_mov_b32 m0, s73
	s_nop 0
	global_load_lds_dwordx4 v[70:71], off
	s_mov_b32 m0, s75
	s_nop 0
	global_load_lds_dwordx4 v[74:75], off
	s_mov_b32 m0, s76
	s_nop 0
	global_load_lds_dwordx4 v[76:77], off
	s_mov_b32 m0, s67
	s_nop 0
	global_load_lds_dwordx4 v[66:67], off
	s_mov_b32 m0, s74
	s_nop 0
	global_load_lds_dwordx4 v[72:73], off
	s_waitcnt vmcnt(8)
	s_waitcnt lgkmcnt(0)
	s_barrier
	s_barrier
	s_cbranch_scc1 .LBB0_487
	s_barrier

.LBB0_652:
	s_add_u32 s8, s10, 0xfffc0080
	s_addc_u32 s9, s11, -1
	s_add_i32 s56, 0, 0x10000
	s_cmp_eq_u32 s93, 12
	s_cselect_b32 s73, s19, s9
	s_cselect_b32 s72, s89, s8
	s_cselect_b32 s67, s21, s92
	s_cselect_b32 s66, s90, s91
	s_add_i32 s57, 0, 0x14000
	v_add_u32_e32 v152, s56, v159
	v_add_u32_e32 v156, s57, v159
	ds_read_b128 v[130:133], v152
	ds_read_b128 v[134:137], v152 offset:1024
	ds_read_b128 v[148:151], v152 offset:2048
	ds_read_b128 v[152:155], v152 offset:3072
	ds_read_b128 v[162:165], v156
	ds_read_b128 v[166:169], v156 offset:1024
	ds_read_b128 v[170:173], v156 offset:2048
	ds_read_b128 v[174:177], v156 offset:3072
	v_lshl_add_u64 v[156:157], s[10:11], 0, v[144:145]
	s_add_i32 m0, s75, 0xc000
	ds_read_b128 v[178:181], v161
	ds_read_b128 v[182:185], v161 offset:1024
	ds_read_b128 v[186:189], v161 offset:2048
	ds_read_b128 v[190:193], v161 offset:3072
	ds_read_b128 v[194:197], v161 offset:4096
	ds_read_b128 v[198:201], v161 offset:5120
	ds_read_b128 v[202:205], v161 offset:6144
	ds_read_b128 v[206:209], v161 offset:7168
	global_load_lds_dwordx4 v[156:157], off
	v_lshl_add_u64 v[156:157], s[10:11], 0, v[146:147]
	s_add_i32 m0, s75, 0xe000
	s_nop 0
	global_load_lds_dwordx4 v[156:157], off
	s_waitcnt vmcnt(8)
	s_waitcnt lgkmcnt(0)
	s_barrier
	s_waitcnt lgkmcnt(0)
	v_mfma_f32_16x16x32_bf16 v[126:129], v[130:133], v[178:181], v[126:129]
	v_mfma_f32_16x16x32_bf16 v[122:125], v[148:151], v[178:181], v[122:125]
	v_mfma_f32_16x16x32_bf16 v[110:113], v[130:133], v[186:189], v[110:113]
	v_mfma_f32_16x16x32_bf16 v[106:109], v[148:151], v[186:189], v[106:109]
	v_mfma_f32_16x16x32_bf16 v[94:97], v[130:133], v[194:197], v[94:97]
	v_mfma_f32_16x16x32_bf16 v[90:93], v[148:151], v[194:197], v[90:93]
	v_mfma_f32_16x16x32_bf16 v[78:81], v[130:133], v[202:205], v[78:81]
	v_mfma_f32_16x16x32_bf16 v[74:77], v[148:151], v[202:205], v[74:77]
	v_mfma_f32_16x16x32_bf16 v[126:129], v[134:137], v[182:185], v[126:129]
	v_mfma_f32_16x16x32_bf16 v[122:125], v[152:155], v[182:185], v[122:125]
	v_mfma_f32_16x16x32_bf16 v[110:113], v[134:137], v[190:193], v[110:113]
	v_mfma_f32_16x16x32_bf16 v[106:109], v[152:155], v[190:193], v[106:109]
	v_mfma_f32_16x16x32_bf16 v[94:97], v[134:137], v[198:201], v[94:97]
	v_mfma_f32_16x16x32_bf16 v[90:93], v[152:155], v[198:201], v[90:93]
	v_mfma_f32_16x16x32_bf16 v[78:81], v[134:137], v[206:209], v[78:81]
	v_mfma_f32_16x16x32_bf16 v[74:77], v[152:155], v[206:209], v[74:77]
	v_mfma_f32_16x16x32_bf16 v[118:121], v[162:165], v[178:181], v[118:121]
	v_mfma_f32_16x16x32_bf16 v[114:117], v[170:173], v[178:181], v[114:117]
	v_mfma_f32_16x16x32_bf16 v[102:105], v[162:165], v[186:189], v[102:105]
	v_mfma_f32_16x16x32_bf16 v[98:101], v[170:173], v[186:189], v[98:101]
	v_mfma_f32_16x16x32_bf16 v[86:89], v[162:165], v[194:197], v[86:89]
	v_mfma_f32_16x16x32_bf16 v[82:85], v[170:173], v[194:197], v[82:85]
	v_mfma_f32_16x16x32_bf16 v[70:73], v[162:165], v[202:205], v[70:73]
	v_mfma_f32_16x16x32_bf16 v[66:69], v[170:173], v[202:205], v[66:69]
	v_mfma_f32_16x16x32_bf16 v[118:121], v[166:169], v[182:185], v[118:121]
	v_mfma_f32_16x16x32_bf16 v[114:117], v[174:177], v[182:185], v[114:117]
	v_mfma_f32_16x16x32_bf16 v[102:105], v[166:169], v[190:193], v[102:105]
	v_mfma_f32_16x16x32_bf16 v[98:101], v[174:177], v[190:193], v[98:101]
	v_mfma_f32_16x16x32_bf16 v[86:89], v[166:169], v[198:201], v[86:89]
	v_mfma_f32_16x16x32_bf16 v[82:85], v[174:177], v[198:201], v[82:85]
	v_mfma_f32_16x16x32_bf16 v[70:73], v[166:169], v[206:209], v[70:73]
	v_mfma_f32_16x16x32_bf16 v[66:69], v[174:177], v[206:209], v[66:69]
	s_barrier
	s_add_i32 s8, s56, s74
	v_lshl_add_u64 v[156:157], s[66:67], 0, v[32:33]
	s_mov_b32 m0, s8
	ds_read_b128 v[178:181], v161 offset:16384
	ds_read_b128 v[182:185], v161 offset:17408
	ds_read_b128 v[186:189], v161 offset:18432
	ds_read_b128 v[190:193], v161 offset:19456
	ds_read_b128 v[194:197], v161 offset:20480
	ds_read_b128 v[198:201], v161 offset:21504
	ds_read_b128 v[202:205], v161 offset:22528
	ds_read_b128 v[206:209], v161 offset:23552
	global_load_lds_dwordx4 v[156:157], off
	s_add_i32 m0, s8, 0x2000
	s_add_u32 s8, s66, 0x40000
	v_lshl_add_u64 v[210:211], s[66:67], 0, v[138:139]
	s_addc_u32 s9, s67, 0
	s_add_i32 s56, s57, s74
	global_load_lds_dwordx4 v[210:211], off
	v_lshl_add_u64 v[212:213], s[8:9], 0, v[32:33]
	s_mov_b32 m0, s56
	v_lshl_add_u64 v[214:215], s[72:73], 0, v[140:141]
	global_load_lds_dwordx4 v[212:213], off
	v_lshl_add_u64 v[212:213], s[8:9], 0, v[138:139]
	s_add_i32 m0, s56, 0x2000
	s_nop 0
	global_load_lds_dwordx4 v[212:213], off
	v_lshl_add_u64 v[212:213], s[72:73], 0, v[142:143]
	s_mov_b32 m0, s75
	s_nop 0
	global_load_lds_dwordx4 v[212:213], off
	s_mov_b32 m0, s76
	s_nop 0
	global_load_lds_dwordx4 v[214:215], off
	s_waitcnt vmcnt(8)
	s_waitcnt lgkmcnt(0)
	s_barrier
	s_waitcnt lgkmcnt(0)
	v_mfma_f32_16x16x32_bf16 v[62:65], v[130:133], v[178:181], v[62:65]
	v_mfma_f32_16x16x32_bf16 v[58:61], v[148:151], v[178:181], v[58:61]
	v_mfma_f32_16x16x32_bf16 v[46:49], v[130:133], v[186:189], v[46:49]
	v_mfma_f32_16x16x32_bf16 v[42:45], v[148:151], v[186:189], v[42:45]
	v_mfma_f32_16x16x32_bf16 v[28:31], v[130:133], v[194:197], v[28:31]
	v_mfma_f32_16x16x32_bf16 v[24:27], v[148:151], v[194:197], v[24:27]
	v_mfma_f32_16x16x32_bf16 v[12:15], v[130:133], v[202:205], v[12:15]
	v_mfma_f32_16x16x32_bf16 v[8:11], v[148:151], v[202:205], v[8:11]
	v_mfma_f32_16x16x32_bf16 v[62:65], v[134:137], v[182:185], v[62:65]
	v_mfma_f32_16x16x32_bf16 v[58:61], v[152:155], v[182:185], v[58:61]
	v_mfma_f32_16x16x32_bf16 v[46:49], v[134:137], v[190:193], v[46:49]
	v_mfma_f32_16x16x32_bf16 v[42:45], v[152:155], v[190:193], v[42:45]
	v_mfma_f32_16x16x32_bf16 v[28:31], v[134:137], v[198:201], v[28:31]
	v_mfma_f32_16x16x32_bf16 v[24:27], v[152:155], v[198:201], v[24:27]
	v_mfma_f32_16x16x32_bf16 v[12:15], v[134:137], v[206:209], v[12:15]
	v_mfma_f32_16x16x32_bf16 v[8:11], v[152:155], v[206:209], v[8:11]
	v_mfma_f32_16x16x32_bf16 v[54:57], v[162:165], v[178:181], v[54:57]
	v_mfma_f32_16x16x32_bf16 v[50:53], v[170:173], v[178:181], v[50:53]
	v_mfma_f32_16x16x32_bf16 v[38:41], v[162:165], v[186:189], v[38:41]
	v_mfma_f32_16x16x32_bf16 v[34:37], v[170:173], v[186:189], v[34:37]
	v_mfma_f32_16x16x32_bf16 v[20:23], v[162:165], v[194:197], v[20:23]
	v_mfma_f32_16x16x32_bf16 v[16:19], v[170:173], v[194:197], v[16:19]
	v_mfma_f32_16x16x32_bf16 v[4:7], v[162:165], v[202:205], v[4:7]
	v_mfma_f32_16x16x32_bf16 v[0:3], v[170:173], v[202:205], v[0:3]
	v_mfma_f32_16x16x32_bf16 v[54:57], v[166:169], v[182:185], v[54:57]
	v_mfma_f32_16x16x32_bf16 v[50:53], v[174:177], v[182:185], v[50:53]
	v_mfma_f32_16x16x32_bf16 v[38:41], v[166:169], v[190:193], v[38:41]
	v_mfma_f32_16x16x32_bf16 v[34:37], v[174:177], v[190:193], v[34:37]
	v_mfma_f32_16x16x32_bf16 v[20:23], v[166:169], v[198:201], v[20:23]
	v_mfma_f32_16x16x32_bf16 v[16:19], v[174:177], v[198:201], v[16:19]
	v_mfma_f32_16x16x32_bf16 v[4:7], v[166:169], v[206:209], v[4:7]
	v_mfma_f32_16x16x32_bf16 v[0:3], v[174:177], v[206:209], v[0:3]
	s_barrier
	s_add_i32 s56, 0, 0x18000
	s_add_i32 s57, 0, 0x1c000
	v_add_u32_e32 v152, s56, v159
	v_add_u32_e32 v174, s57, v159
	ds_read_b128 v[130:133], v152
	ds_read_b128 v[134:137], v152 offset:1024
	ds_read_b128 v[148:151], v152 offset:2048
	ds_read_b128 v[152:155], v152 offset:3072
	ds_read_b128 v[162:165], v174
	ds_read_b128 v[166:169], v174 offset:1024
	ds_read_b128 v[170:173], v174 offset:2048
	ds_read_b128 v[174:177], v174 offset:3072
	s_add_u32 s8, s72, 0x40000
	s_addc_u32 s9, s73, 0
	s_mov_b32 m0, s77
	v_lshl_add_u64 v[216:217], s[8:9], 0, v[142:143]
	ds_read_b128 v[178:181], v161 offset:32768
	ds_read_b128 v[182:185], v161 offset:33792
	ds_read_b128 v[186:189], v161 offset:34816
	ds_read_b128 v[190:193], v161 offset:35840
	ds_read_b128 v[194:197], v161 offset:36864
	ds_read_b128 v[198:201], v161 offset:37888
	ds_read_b128 v[202:205], v161 offset:38912
	ds_read_b128 v[206:209], v161 offset:39936
	global_load_lds_dwordx4 v[216:217], off
	v_lshl_add_u64 v[216:217], s[8:9], 0, v[140:141]
	s_mov_b32 m0, s83
	s_nop 0
	global_load_lds_dwordx4 v[216:217], off
	s_waitcnt vmcnt(8)
	s_waitcnt lgkmcnt(0)
	s_barrier
	s_waitcnt lgkmcnt(0)
	v_mfma_f32_16x16x32_bf16 v[126:129], v[130:133], v[178:181], v[126:129]
	v_mfma_f32_16x16x32_bf16 v[122:125], v[148:151], v[178:181], v[122:125]
	v_mfma_f32_16x16x32_bf16 v[110:113], v[130:133], v[186:189], v[110:113]
	v_mfma_f32_16x16x32_bf16 v[106:109], v[148:151], v[186:189], v[106:109]
	v_mfma_f32_16x16x32_bf16 v[94:97], v[130:133], v[194:197], v[94:97]
	v_mfma_f32_16x16x32_bf16 v[90:93], v[148:151], v[194:197], v[90:93]
	v_mfma_f32_16x16x32_bf16 v[78:81], v[130:133], v[202:205], v[78:81]
	v_mfma_f32_16x16x32_bf16 v[74:77], v[148:151], v[202:205], v[74:77]
	v_mfma_f32_16x16x32_bf16 v[126:129], v[134:137], v[182:185], v[126:129]
	v_mfma_f32_16x16x32_bf16 v[122:125], v[152:155], v[182:185], v[122:125]
	v_mfma_f32_16x16x32_bf16 v[110:113], v[134:137], v[190:193], v[110:113]
	v_mfma_f32_16x16x32_bf16 v[106:109], v[152:155], v[190:193], v[106:109]
	v_mfma_f32_16x16x32_bf16 v[94:97], v[134:137], v[198:201], v[94:97]
	v_mfma_f32_16x16x32_bf16 v[90:93], v[152:155], v[198:201], v[90:93]
	v_mfma_f32_16x16x32_bf16 v[78:81], v[134:137], v[206:209], v[78:81]
	v_mfma_f32_16x16x32_bf16 v[74:77], v[152:155], v[206:209], v[74:77]
	v_mfma_f32_16x16x32_bf16 v[118:121], v[162:165], v[178:181], v[118:121]
	v_mfma_f32_16x16x32_bf16 v[114:117], v[170:173], v[178:181], v[114:117]
	v_mfma_f32_16x16x32_bf16 v[102:105], v[162:165], v[186:189], v[102:105]
	v_mfma_f32_16x16x32_bf16 v[98:101], v[170:173], v[186:189], v[98:101]
	v_mfma_f32_16x16x32_bf16 v[86:89], v[162:165], v[194:197], v[86:89]
	v_mfma_f32_16x16x32_bf16 v[82:85], v[170:173], v[194:197], v[82:85]
	v_mfma_f32_16x16x32_bf16 v[70:73], v[162:165], v[202:205], v[70:73]
	v_mfma_f32_16x16x32_bf16 v[66:69], v[170:173], v[202:205], v[66:69]
	v_mfma_f32_16x16x32_bf16 v[118:121], v[166:169], v[182:185], v[118:121]
	v_mfma_f32_16x16x32_bf16 v[114:117], v[174:177], v[182:185], v[114:117]
	v_mfma_f32_16x16x32_bf16 v[102:105], v[166:169], v[190:193], v[102:105]
	v_mfma_f32_16x16x32_bf16 v[98:101], v[174:177], v[190:193], v[98:101]
	v_mfma_f32_16x16x32_bf16 v[86:89], v[166:169], v[198:201], v[86:89]
	v_mfma_f32_16x16x32_bf16 v[82:85], v[174:177], v[198:201], v[82:85]
	v_mfma_f32_16x16x32_bf16 v[70:73], v[166:169], v[206:209], v[70:73]
	v_mfma_f32_16x16x32_bf16 v[66:69], v[174:177], v[206:209], v[66:69]
	s_barrier
	s_add_i32 s8, s56, s74
	v_lshl_add_u64 v[156:157], v[156:157], 0, s[38:39]
	s_mov_b32 m0, s8
	ds_read_b128 v[178:181], v161 offset:49152
	ds_read_b128 v[182:185], v161 offset:50176
	ds_read_b128 v[186:189], v161 offset:51200
	ds_read_b128 v[190:193], v161 offset:52224
	ds_read_b128 v[194:197], v161 offset:53248
	ds_read_b128 v[198:201], v161 offset:54272
	ds_read_b128 v[202:205], v161 offset:55296
	ds_read_b128 v[206:209], v161 offset:56320
	global_load_lds_dwordx4 v[156:157], off
	s_add_i32 m0, s8, 0x2000
	s_add_u32 s8, s66, 0x40080
	v_lshl_add_u64 v[156:157], v[210:211], 0, s[38:39]
	s_addc_u32 s9, s67, 0
	s_add_i32 s56, s57, s74
	global_load_lds_dwordx4 v[156:157], off
	v_lshl_add_u64 v[156:157], s[8:9], 0, v[32:33]
	s_mov_b32 m0, s56
	s_nop 0
	global_load_lds_dwordx4 v[156:157], off
	v_lshl_add_u64 v[156:157], s[8:9], 0, v[138:139]
	s_add_i32 m0, s56, 0x2000
	s_nop 0
	global_load_lds_dwordx4 v[156:157], off
	v_lshl_add_u64 v[156:157], v[212:213], 0, s[38:39]
	s_mov_b32 m0, s84
	s_nop 0
	global_load_lds_dwordx4 v[156:157], off
	v_lshl_add_u64 v[156:157], v[214:215], 0, s[38:39]
	s_mov_b32 m0, s85
	s_nop 0
	global_load_lds_dwordx4 v[156:157], off
	s_waitcnt vmcnt(8)
	s_waitcnt lgkmcnt(0)
	s_barrier
	s_waitcnt lgkmcnt(0)
	v_mfma_f32_16x16x32_bf16 v[62:65], v[130:133], v[178:181], v[62:65]
	v_mfma_f32_16x16x32_bf16 v[58:61], v[148:151], v[178:181], v[58:61]
	v_mfma_f32_16x16x32_bf16 v[46:49], v[130:133], v[186:189], v[46:49]
	v_mfma_f32_16x16x32_bf16 v[42:45], v[148:151], v[186:189], v[42:45]
	v_mfma_f32_16x16x32_bf16 v[28:31], v[130:133], v[194:197], v[28:31]
	v_mfma_f32_16x16x32_bf16 v[24:27], v[148:151], v[194:197], v[24:27]
	v_mfma_f32_16x16x32_bf16 v[12:15], v[130:133], v[202:205], v[12:15]
	v_mfma_f32_16x16x32_bf16 v[8:11], v[148:151], v[202:205], v[8:11]
	v_mfma_f32_16x16x32_bf16 v[62:65], v[134:137], v[182:185], v[62:65]
	v_mfma_f32_16x16x32_bf16 v[58:61], v[152:155], v[182:185], v[58:61]
	v_mfma_f32_16x16x32_bf16 v[46:49], v[134:137], v[190:193], v[46:49]
	v_mfma_f32_16x16x32_bf16 v[42:45], v[152:155], v[190:193], v[42:45]
	v_mfma_f32_16x16x32_bf16 v[28:31], v[134:137], v[198:201], v[28:31]
	v_mfma_f32_16x16x32_bf16 v[24:27], v[152:155], v[198:201], v[24:27]
	v_mfma_f32_16x16x32_bf16 v[12:15], v[134:137], v[206:209], v[12:15]
	v_mfma_f32_16x16x32_bf16 v[8:11], v[152:155], v[206:209], v[8:11]
	v_mfma_f32_16x16x32_bf16 v[54:57], v[162:165], v[178:181], v[54:57]
	v_mfma_f32_16x16x32_bf16 v[50:53], v[170:173], v[178:181], v[50:53]
	v_mfma_f32_16x16x32_bf16 v[38:41], v[162:165], v[186:189], v[38:41]
	v_mfma_f32_16x16x32_bf16 v[34:37], v[170:173], v[186:189], v[34:37]
	v_mfma_f32_16x16x32_bf16 v[20:23], v[162:165], v[194:197], v[20:23]
	v_mfma_f32_16x16x32_bf16 v[16:19], v[170:173], v[194:197], v[16:19]
	v_mfma_f32_16x16x32_bf16 v[4:7], v[162:165], v[202:205], v[4:7]
	v_mfma_f32_16x16x32_bf16 v[0:3], v[170:173], v[202:205], v[0:3]
	v_mfma_f32_16x16x32_bf16 v[54:57], v[166:169], v[182:185], v[54:57]
	v_mfma_f32_16x16x32_bf16 v[50:53], v[174:177], v[182:185], v[50:53]
	v_mfma_f32_16x16x32_bf16 v[38:41], v[166:169], v[190:193], v[38:41]
	v_mfma_f32_16x16x32_bf16 v[34:37], v[174:177], v[190:193], v[34:37]
	v_mfma_f32_16x16x32_bf16 v[20:23], v[166:169], v[198:201], v[20:23]
	v_mfma_f32_16x16x32_bf16 v[16:19], v[174:177], v[198:201], v[16:19]
	v_mfma_f32_16x16x32_bf16 v[4:7], v[166:169], v[206:209], v[4:7]
	v_mfma_f32_16x16x32_bf16 v[0:3], v[174:177], v[206:209], v[0:3]
	s_barrier
	s_add_i32 s93, s93, 2
	s_add_u32 s10, s10, 0x100
	s_addc_u32 s11, s11, 0
	s_add_u32 s91, s91, 0x100
	s_addc_u32 s92, s92, 0
	s_cmp_gt_u32 s93, 13
	s_cbranch_scc0 .LBB0_652
	s_and_b64 vcc, exec, s[16:17]
	s_cbranch_vccz .LBB0_655
	s_barrier

.LBB0_1534:
	s_add_u32 s14, s72, 0x100
	s_addc_u32 s15, s73, 0
	s_add_i32 s9, 0, 0x10000
	s_cmp_eq_u32 s8, 4
	s_cselect_b32 s77, s45, s15
	s_cselect_b32 s76, s44, s14
	s_cselect_b32 s75, s35, s97
	s_cselect_b32 s74, vcc_lo, s96
	s_add_i32 s56, 0, 0x14000
	v_add_u32_e32 v142, s9, v205
	v_add_u32_e32 v158, s56, v205
	ds_read_b128 v[130:133], v142
	ds_read_b128 v[134:137], v142 offset:1024
	ds_read_b128 v[138:141], v142 offset:2048
	ds_read_b128 v[142:145], v142 offset:3072
	ds_read_b128 v[146:149], v158
	ds_read_b128 v[150:153], v158 offset:1024
	ds_read_b128 v[154:157], v158 offset:2048
	ds_read_b128 v[158:161], v158 offset:3072
	v_lshl_add_u64 v[208:209], s[72:73], 0, v[172:173]
	s_add_i32 m0, s85, 0xc000
	ds_read_b128 v[162:165], v207
	ds_read_b128 v[176:179], v207 offset:1024
	ds_read_b128 v[180:183], v207 offset:2048
	ds_read_b128 v[184:187], v207 offset:3072
	ds_read_b128 v[188:191], v207 offset:4096
	ds_read_b128 v[192:195], v207 offset:5120
	ds_read_b128 v[196:199], v207 offset:6144
	ds_read_b128 v[200:203], v207 offset:7168
	global_load_lds_dwordx4 v[208:209], off
	v_lshl_add_u64 v[208:209], s[72:73], 0, v[174:175]
	s_add_i32 m0, s85, 0xe000
	s_nop 0
	global_load_lds_dwordx4 v[208:209], off
	s_waitcnt vmcnt(8)
	s_waitcnt lgkmcnt(0)
	s_barrier
	s_waitcnt lgkmcnt(0)
	v_mfma_f32_16x16x32_bf16 v[126:129], v[130:133], v[162:165], v[126:129]
	v_mfma_f32_16x16x32_bf16 v[122:125], v[138:141], v[162:165], v[122:125]
	v_mfma_f32_16x16x32_bf16 v[110:113], v[130:133], v[180:183], v[110:113]
	v_mfma_f32_16x16x32_bf16 v[106:109], v[138:141], v[180:183], v[106:109]
	v_mfma_f32_16x16x32_bf16 v[94:97], v[130:133], v[188:191], v[94:97]
	v_mfma_f32_16x16x32_bf16 v[90:93], v[138:141], v[188:191], v[90:93]
	v_mfma_f32_16x16x32_bf16 v[78:81], v[130:133], v[196:199], v[78:81]
	v_mfma_f32_16x16x32_bf16 v[74:77], v[138:141], v[196:199], v[74:77]
	v_mfma_f32_16x16x32_bf16 v[126:129], v[134:137], v[176:179], v[126:129]
	v_mfma_f32_16x16x32_bf16 v[122:125], v[142:145], v[176:179], v[122:125]
	v_mfma_f32_16x16x32_bf16 v[110:113], v[134:137], v[184:187], v[110:113]
	v_mfma_f32_16x16x32_bf16 v[106:109], v[142:145], v[184:187], v[106:109]
	v_mfma_f32_16x16x32_bf16 v[94:97], v[134:137], v[192:195], v[94:97]
	v_mfma_f32_16x16x32_bf16 v[90:93], v[142:145], v[192:195], v[90:93]
	v_mfma_f32_16x16x32_bf16 v[78:81], v[134:137], v[200:203], v[78:81]
	v_mfma_f32_16x16x32_bf16 v[74:77], v[142:145], v[200:203], v[74:77]
	v_mfma_f32_16x16x32_bf16 v[118:121], v[146:149], v[162:165], v[118:121]
	v_mfma_f32_16x16x32_bf16 v[114:117], v[154:157], v[162:165], v[114:117]
	v_mfma_f32_16x16x32_bf16 v[102:105], v[146:149], v[180:183], v[102:105]
	v_mfma_f32_16x16x32_bf16 v[98:101], v[154:157], v[180:183], v[98:101]
	v_mfma_f32_16x16x32_bf16 v[86:89], v[146:149], v[188:191], v[86:89]
	v_mfma_f32_16x16x32_bf16 v[82:85], v[154:157], v[188:191], v[82:85]
	v_mfma_f32_16x16x32_bf16 v[70:73], v[146:149], v[196:199], v[70:73]
	v_mfma_f32_16x16x32_bf16 v[66:69], v[154:157], v[196:199], v[66:69]
	v_mfma_f32_16x16x32_bf16 v[118:121], v[150:153], v[176:179], v[118:121]
	v_mfma_f32_16x16x32_bf16 v[114:117], v[158:161], v[176:179], v[114:117]
	v_mfma_f32_16x16x32_bf16 v[102:105], v[150:153], v[184:187], v[102:105]
	v_mfma_f32_16x16x32_bf16 v[98:101], v[158:161], v[184:187], v[98:101]
	v_mfma_f32_16x16x32_bf16 v[86:89], v[150:153], v[192:195], v[86:89]
	v_mfma_f32_16x16x32_bf16 v[82:85], v[158:161], v[192:195], v[82:85]
	v_mfma_f32_16x16x32_bf16 v[70:73], v[150:153], v[200:203], v[70:73]
	v_mfma_f32_16x16x32_bf16 v[66:69], v[158:161], v[200:203], v[66:69]
	s_barrier
	s_add_i32 s9, s9, s84
	v_lshl_add_u64 v[208:209], s[74:75], 0, v[32:33]
	s_mov_b32 m0, s9
	ds_read_b128 v[162:165], v207 offset:16384
	ds_read_b128 v[176:179], v207 offset:17408
	ds_read_b128 v[180:183], v207 offset:18432
	ds_read_b128 v[184:187], v207 offset:19456
	ds_read_b128 v[188:191], v207 offset:20480
	ds_read_b128 v[192:195], v207 offset:21504
	ds_read_b128 v[196:199], v207 offset:22528
	ds_read_b128 v[200:203], v207 offset:23552
	global_load_lds_dwordx4 v[208:209], off
	s_add_i32 m0, s9, 0x2000
	s_add_u32 s72, s74, 0x20000
	v_lshl_add_u64 v[210:211], s[74:75], 0, v[166:167]
	s_addc_u32 s73, s75, 0
	s_add_i32 s9, s56, s84
	global_load_lds_dwordx4 v[210:211], off
	v_lshl_add_u64 v[212:213], s[72:73], 0, v[32:33]
	s_mov_b32 m0, s9
	v_lshl_add_u64 v[214:215], s[76:77], 0, v[168:169]
	global_load_lds_dwordx4 v[212:213], off
	v_lshl_add_u64 v[212:213], s[72:73], 0, v[166:167]
	s_add_i32 m0, s9, 0x2000
	s_nop 0
	global_load_lds_dwordx4 v[212:213], off
	v_lshl_add_u64 v[212:213], s[76:77], 0, v[170:171]
	s_mov_b32 m0, s85
	s_nop 0
	global_load_lds_dwordx4 v[212:213], off
	s_mov_b32 m0, s86
	s_nop 0
	global_load_lds_dwordx4 v[214:215], off
	s_waitcnt vmcnt(8)
	s_waitcnt lgkmcnt(0)
	s_barrier
	s_waitcnt lgkmcnt(0)
	v_mfma_f32_16x16x32_bf16 v[62:65], v[130:133], v[162:165], v[62:65]
	v_mfma_f32_16x16x32_bf16 v[58:61], v[138:141], v[162:165], v[58:61]
	v_mfma_f32_16x16x32_bf16 v[46:49], v[130:133], v[180:183], v[46:49]
	v_mfma_f32_16x16x32_bf16 v[42:45], v[138:141], v[180:183], v[42:45]
	v_mfma_f32_16x16x32_bf16 v[28:31], v[130:133], v[188:191], v[28:31]
	v_mfma_f32_16x16x32_bf16 v[24:27], v[138:141], v[188:191], v[24:27]
	v_mfma_f32_16x16x32_bf16 v[12:15], v[130:133], v[196:199], v[12:15]
	v_mfma_f32_16x16x32_bf16 v[8:11], v[138:141], v[196:199], v[8:11]
	v_mfma_f32_16x16x32_bf16 v[62:65], v[134:137], v[176:179], v[62:65]
	v_mfma_f32_16x16x32_bf16 v[58:61], v[142:145], v[176:179], v[58:61]
	v_mfma_f32_16x16x32_bf16 v[46:49], v[134:137], v[184:187], v[46:49]
	v_mfma_f32_16x16x32_bf16 v[42:45], v[142:145], v[184:187], v[42:45]
	v_mfma_f32_16x16x32_bf16 v[28:31], v[134:137], v[192:195], v[28:31]
	v_mfma_f32_16x16x32_bf16 v[24:27], v[142:145], v[192:195], v[24:27]
	v_mfma_f32_16x16x32_bf16 v[12:15], v[134:137], v[200:203], v[12:15]
	v_mfma_f32_16x16x32_bf16 v[8:11], v[142:145], v[200:203], v[8:11]
	v_mfma_f32_16x16x32_bf16 v[54:57], v[146:149], v[162:165], v[54:57]
	v_mfma_f32_16x16x32_bf16 v[50:53], v[154:157], v[162:165], v[50:53]
	v_mfma_f32_16x16x32_bf16 v[38:41], v[146:149], v[180:183], v[38:41]
	v_mfma_f32_16x16x32_bf16 v[34:37], v[154:157], v[180:183], v[34:37]
	v_mfma_f32_16x16x32_bf16 v[20:23], v[146:149], v[188:191], v[20:23]
	v_mfma_f32_16x16x32_bf16 v[16:19], v[154:157], v[188:191], v[16:19]
	v_mfma_f32_16x16x32_bf16 v[4:7], v[146:149], v[196:199], v[4:7]
	v_mfma_f32_16x16x32_bf16 v[0:3], v[154:157], v[196:199], v[0:3]
	v_mfma_f32_16x16x32_bf16 v[54:57], v[150:153], v[176:179], v[54:57]
	v_mfma_f32_16x16x32_bf16 v[50:53], v[158:161], v[176:179], v[50:53]
	v_mfma_f32_16x16x32_bf16 v[38:41], v[150:153], v[184:187], v[38:41]
	v_mfma_f32_16x16x32_bf16 v[34:37], v[158:161], v[184:187], v[34:37]
	v_mfma_f32_16x16x32_bf16 v[20:23], v[150:153], v[192:195], v[20:23]
	v_mfma_f32_16x16x32_bf16 v[16:19], v[158:161], v[192:195], v[16:19]
	v_mfma_f32_16x16x32_bf16 v[4:7], v[150:153], v[200:203], v[4:7]
	v_mfma_f32_16x16x32_bf16 v[0:3], v[158:161], v[200:203], v[0:3]
	s_barrier
	s_add_i32 s9, 0, 0x18000
	s_add_i32 s56, 0, 0x1c000
	v_add_u32_e32 v142, s9, v205
	v_add_u32_e32 v158, s56, v205
	ds_read_b128 v[130:133], v142
	ds_read_b128 v[134:137], v142 offset:1024
	ds_read_b128 v[138:141], v142 offset:2048
	ds_read_b128 v[142:145], v142 offset:3072
	ds_read_b128 v[146:149], v158
	ds_read_b128 v[150:153], v158 offset:1024
	ds_read_b128 v[154:157], v158 offset:2048
	ds_read_b128 v[158:161], v158 offset:3072
	s_add_u32 s72, s76, 0x2a0000
	s_addc_u32 s73, s77, 0
	s_mov_b32 m0, s87
	v_lshl_add_u64 v[216:217], s[72:73], 0, v[170:171]
	ds_read_b128 v[162:165], v207 offset:32768
	ds_read_b128 v[176:179], v207 offset:33792
	ds_read_b128 v[180:183], v207 offset:34816
	ds_read_b128 v[184:187], v207 offset:35840
	ds_read_b128 v[188:191], v207 offset:36864
	ds_read_b128 v[192:195], v207 offset:37888
	ds_read_b128 v[196:199], v207 offset:38912
	ds_read_b128 v[200:203], v207 offset:39936
	global_load_lds_dwordx4 v[216:217], off
	v_lshl_add_u64 v[216:217], s[72:73], 0, v[168:169]
	s_mov_b32 m0, s88
	s_nop 0
	global_load_lds_dwordx4 v[216:217], off
	s_waitcnt vmcnt(8)
	s_waitcnt lgkmcnt(0)
	s_barrier
	s_waitcnt lgkmcnt(0)
	v_mfma_f32_16x16x32_bf16 v[126:129], v[130:133], v[162:165], v[126:129]
	v_mfma_f32_16x16x32_bf16 v[122:125], v[138:141], v[162:165], v[122:125]
	v_mfma_f32_16x16x32_bf16 v[110:113], v[130:133], v[180:183], v[110:113]
	v_mfma_f32_16x16x32_bf16 v[106:109], v[138:141], v[180:183], v[106:109]
	v_mfma_f32_16x16x32_bf16 v[94:97], v[130:133], v[188:191], v[94:97]
	v_mfma_f32_16x16x32_bf16 v[90:93], v[138:141], v[188:191], v[90:93]
	v_mfma_f32_16x16x32_bf16 v[78:81], v[130:133], v[196:199], v[78:81]
	v_mfma_f32_16x16x32_bf16 v[74:77], v[138:141], v[196:199], v[74:77]
	v_mfma_f32_16x16x32_bf16 v[126:129], v[134:137], v[176:179], v[126:129]
	v_mfma_f32_16x16x32_bf16 v[122:125], v[142:145], v[176:179], v[122:125]
	v_mfma_f32_16x16x32_bf16 v[110:113], v[134:137], v[184:187], v[110:113]
	v_mfma_f32_16x16x32_bf16 v[106:109], v[142:145], v[184:187], v[106:109]
	v_mfma_f32_16x16x32_bf16 v[94:97], v[134:137], v[192:195], v[94:97]
	v_mfma_f32_16x16x32_bf16 v[90:93], v[142:145], v[192:195], v[90:93]
	v_mfma_f32_16x16x32_bf16 v[78:81], v[134:137], v[200:203], v[78:81]
	v_mfma_f32_16x16x32_bf16 v[74:77], v[142:145], v[200:203], v[74:77]
	v_mfma_f32_16x16x32_bf16 v[118:121], v[146:149], v[162:165], v[118:121]
	v_mfma_f32_16x16x32_bf16 v[114:117], v[154:157], v[162:165], v[114:117]
	v_mfma_f32_16x16x32_bf16 v[102:105], v[146:149], v[180:183], v[102:105]
	v_mfma_f32_16x16x32_bf16 v[98:101], v[154:157], v[180:183], v[98:101]
	v_mfma_f32_16x16x32_bf16 v[86:89], v[146:149], v[188:191], v[86:89]
	v_mfma_f32_16x16x32_bf16 v[82:85], v[154:157], v[188:191], v[82:85]
	v_mfma_f32_16x16x32_bf16 v[70:73], v[146:149], v[196:199], v[70:73]
	v_mfma_f32_16x16x32_bf16 v[66:69], v[154:157], v[196:199], v[66:69]
	v_mfma_f32_16x16x32_bf16 v[118:121], v[150:153], v[176:179], v[118:121]
	v_mfma_f32_16x16x32_bf16 v[114:117], v[158:161], v[176:179], v[114:117]
	v_mfma_f32_16x16x32_bf16 v[102:105], v[150:153], v[184:187], v[102:105]
	v_mfma_f32_16x16x32_bf16 v[98:101], v[158:161], v[184:187], v[98:101]
	v_mfma_f32_16x16x32_bf16 v[86:89], v[150:153], v[192:195], v[86:89]
	v_mfma_f32_16x16x32_bf16 v[82:85], v[158:161], v[192:195], v[82:85]
	v_mfma_f32_16x16x32_bf16 v[70:73], v[150:153], v[200:203], v[70:73]
	v_mfma_f32_16x16x32_bf16 v[66:69], v[158:161], v[200:203], v[66:69]
	s_barrier
	s_add_i32 s9, s9, s84
	v_lshl_add_u64 v[208:209], v[208:209], 0, s[38:39]
	s_mov_b32 m0, s9
	ds_read_b128 v[162:165], v207 offset:49152
	ds_read_b128 v[176:179], v207 offset:50176
	ds_read_b128 v[180:183], v207 offset:51200
	ds_read_b128 v[184:187], v207 offset:52224
	ds_read_b128 v[188:191], v207 offset:53248
	ds_read_b128 v[192:195], v207 offset:54272
	ds_read_b128 v[196:199], v207 offset:55296
	ds_read_b128 v[200:203], v207 offset:56320
	global_load_lds_dwordx4 v[208:209], off
	s_add_i32 m0, s9, 0x2000
	s_add_u32 s72, s74, 0x20080
	v_lshl_add_u64 v[208:209], v[210:211], 0, s[38:39]
	s_addc_u32 s73, s75, 0
	s_add_i32 s9, s56, s84
	global_load_lds_dwordx4 v[208:209], off
	v_lshl_add_u64 v[208:209], s[72:73], 0, v[32:33]
	s_mov_b32 m0, s9
	s_nop 0
	global_load_lds_dwordx4 v[208:209], off
	v_lshl_add_u64 v[208:209], s[72:73], 0, v[166:167]
	s_add_i32 m0, s9, 0x2000
	s_nop 0
	global_load_lds_dwordx4 v[208:209], off
	v_lshl_add_u64 v[208:209], v[212:213], 0, s[38:39]
	s_mov_b32 m0, s89
	s_nop 0
	global_load_lds_dwordx4 v[208:209], off
	v_lshl_add_u64 v[208:209], v[214:215], 0, s[38:39]
	s_mov_b32 m0, s90
	s_nop 0
	global_load_lds_dwordx4 v[208:209], off
	s_waitcnt vmcnt(8)
	s_waitcnt lgkmcnt(0)
	s_barrier
	s_waitcnt lgkmcnt(0)
	v_mfma_f32_16x16x32_bf16 v[62:65], v[130:133], v[162:165], v[62:65]
	v_mfma_f32_16x16x32_bf16 v[58:61], v[138:141], v[162:165], v[58:61]
	v_mfma_f32_16x16x32_bf16 v[46:49], v[130:133], v[180:183], v[46:49]
	v_mfma_f32_16x16x32_bf16 v[42:45], v[138:141], v[180:183], v[42:45]
	v_mfma_f32_16x16x32_bf16 v[28:31], v[130:133], v[188:191], v[28:31]
	v_mfma_f32_16x16x32_bf16 v[24:27], v[138:141], v[188:191], v[24:27]
	v_mfma_f32_16x16x32_bf16 v[12:15], v[130:133], v[196:199], v[12:15]
	v_mfma_f32_16x16x32_bf16 v[8:11], v[138:141], v[196:199], v[8:11]
	v_mfma_f32_16x16x32_bf16 v[62:65], v[134:137], v[176:179], v[62:65]
	v_mfma_f32_16x16x32_bf16 v[58:61], v[142:145], v[176:179], v[58:61]
	v_mfma_f32_16x16x32_bf16 v[46:49], v[134:137], v[184:187], v[46:49]
	v_mfma_f32_16x16x32_bf16 v[42:45], v[142:145], v[184:187], v[42:45]
	v_mfma_f32_16x16x32_bf16 v[28:31], v[134:137], v[192:195], v[28:31]
	v_mfma_f32_16x16x32_bf16 v[24:27], v[142:145], v[192:195], v[24:27]
	v_mfma_f32_16x16x32_bf16 v[12:15], v[134:137], v[200:203], v[12:15]
	v_mfma_f32_16x16x32_bf16 v[8:11], v[142:145], v[200:203], v[8:11]
	v_mfma_f32_16x16x32_bf16 v[54:57], v[146:149], v[162:165], v[54:57]
	v_mfma_f32_16x16x32_bf16 v[50:53], v[154:157], v[162:165], v[50:53]
	v_mfma_f32_16x16x32_bf16 v[38:41], v[146:149], v[180:183], v[38:41]
	v_mfma_f32_16x16x32_bf16 v[34:37], v[154:157], v[180:183], v[34:37]
	v_mfma_f32_16x16x32_bf16 v[20:23], v[146:149], v[188:191], v[20:23]
	v_mfma_f32_16x16x32_bf16 v[16:19], v[154:157], v[188:191], v[16:19]
	v_mfma_f32_16x16x32_bf16 v[4:7], v[146:149], v[196:199], v[4:7]
	v_mfma_f32_16x16x32_bf16 v[0:3], v[154:157], v[196:199], v[0:3]
	v_mfma_f32_16x16x32_bf16 v[54:57], v[150:153], v[176:179], v[54:57]
	v_mfma_f32_16x16x32_bf16 v[50:53], v[158:161], v[176:179], v[50:53]
	v_mfma_f32_16x16x32_bf16 v[38:41], v[150:153], v[184:187], v[38:41]
	v_mfma_f32_16x16x32_bf16 v[34:37], v[158:161], v[184:187], v[34:37]
	v_mfma_f32_16x16x32_bf16 v[20:23], v[150:153], v[192:195], v[20:23]
	v_mfma_f32_16x16x32_bf16 v[16:19], v[158:161], v[192:195], v[16:19]
	v_mfma_f32_16x16x32_bf16 v[4:7], v[150:153], v[200:203], v[4:7]
	v_mfma_f32_16x16x32_bf16 v[0:3], v[158:161], v[200:203], v[0:3]
	s_barrier
	s_add_i32 s8, s8, 2
	s_add_u32 s96, s96, 0x100
	s_addc_u32 s97, s97, 0
	s_cmp_gt_u32 s8, 5
	s_mov_b64 s[72:73], s[14:15]
	s_cbranch_scc0 .LBB0_1534
	s_and_b64 vcc, exec, s[18:19]
	s_cbranch_vccz .LBB0_1537
	s_barrier

.LBB0_1640:
	s_add_u32 s9, s14, 0xfffc0080
	s_addc_u32 s56, s15, -1
	s_add_i32 s57, 0, 0x10000
	s_cmp_eq_u32 s8, 12
	s_cselect_b32 vcc_hi, s67, s56
	s_cselect_b32 vcc_lo, s94, s9
	s_cselect_b32 s75, s45, s97
	s_cselect_b32 s74, s95, s96
	s_add_i32 s9, 0, 0x14000
	v_add_u32_e32 v142, s57, v228
	v_add_u32_e32 v158, s9, v228
	ds_read_b128 v[122:125], v142
	ds_read_b128 v[134:137], v142 offset:1024
	ds_read_b128 v[138:141], v142 offset:2048
	ds_read_b128 v[142:145], v142 offset:3072
	ds_read_b128 v[146:149], v158
	ds_read_b128 v[150:153], v158 offset:1024
	ds_read_b128 v[154:157], v158 offset:2048
	ds_read_b128 v[158:161], v158 offset:3072
	v_lshl_add_u64 v[194:195], s[14:15], 0, v[202:203]
	s_add_i32 m0, s86, 0xc000
	ds_read_b128 v[162:165], v230
	ds_read_b128 v[166:169], v230 offset:1024
	ds_read_b128 v[170:173], v230 offset:2048
	ds_read_b128 v[174:177], v230 offset:3072
	ds_read_b128 v[178:181], v230 offset:4096
	ds_read_b128 v[182:185], v230 offset:5120
	ds_read_b128 v[186:189], v230 offset:6144
	ds_read_b128 v[190:193], v230 offset:7168
	global_load_lds_dwordx4 v[194:195], off
	v_lshl_add_u64 v[194:195], s[14:15], 0, v[204:205]
	s_add_i32 m0, s86, 0xe000
	s_nop 0
	global_load_lds_dwordx4 v[194:195], off
	s_waitcnt vmcnt(8)
	s_waitcnt lgkmcnt(0)
	s_barrier
	s_waitcnt lgkmcnt(0)
	v_mfma_f32_16x16x32_bf16 v[130:133], v[122:125], v[162:165], v[130:133]
	v_mfma_f32_16x16x32_bf16 v[126:129], v[138:141], v[162:165], v[126:129]
	v_mfma_f32_16x16x32_bf16 v[110:113], v[122:125], v[170:173], v[110:113]
	v_mfma_f32_16x16x32_bf16 v[106:109], v[138:141], v[170:173], v[106:109]
	v_mfma_f32_16x16x32_bf16 v[94:97], v[122:125], v[178:181], v[94:97]
	v_mfma_f32_16x16x32_bf16 v[90:93], v[138:141], v[178:181], v[90:93]
	v_mfma_f32_16x16x32_bf16 v[78:81], v[122:125], v[186:189], v[78:81]
	v_mfma_f32_16x16x32_bf16 v[74:77], v[138:141], v[186:189], v[74:77]
	v_mfma_f32_16x16x32_bf16 v[130:133], v[134:137], v[166:169], v[130:133]
	v_mfma_f32_16x16x32_bf16 v[126:129], v[142:145], v[166:169], v[126:129]
	v_mfma_f32_16x16x32_bf16 v[110:113], v[134:137], v[174:177], v[110:113]
	v_mfma_f32_16x16x32_bf16 v[106:109], v[142:145], v[174:177], v[106:109]
	v_mfma_f32_16x16x32_bf16 v[94:97], v[134:137], v[182:185], v[94:97]
	v_mfma_f32_16x16x32_bf16 v[90:93], v[142:145], v[182:185], v[90:93]
	v_mfma_f32_16x16x32_bf16 v[78:81], v[134:137], v[190:193], v[78:81]
	v_mfma_f32_16x16x32_bf16 v[74:77], v[142:145], v[190:193], v[74:77]
	v_mfma_f32_16x16x32_bf16 v[118:121], v[146:149], v[162:165], v[118:121]
	v_mfma_f32_16x16x32_bf16 v[114:117], v[154:157], v[162:165], v[114:117]
	v_mfma_f32_16x16x32_bf16 v[102:105], v[146:149], v[170:173], v[102:105]
	v_mfma_f32_16x16x32_bf16 v[98:101], v[154:157], v[170:173], v[98:101]
	v_mfma_f32_16x16x32_bf16 v[86:89], v[146:149], v[178:181], v[86:89]
	v_mfma_f32_16x16x32_bf16 v[82:85], v[154:157], v[178:181], v[82:85]
	v_mfma_f32_16x16x32_bf16 v[70:73], v[146:149], v[186:189], v[70:73]
	v_mfma_f32_16x16x32_bf16 v[66:69], v[154:157], v[186:189], v[66:69]
	v_mfma_f32_16x16x32_bf16 v[118:121], v[150:153], v[166:169], v[118:121]
	v_mfma_f32_16x16x32_bf16 v[114:117], v[158:161], v[166:169], v[114:117]
	v_mfma_f32_16x16x32_bf16 v[102:105], v[150:153], v[174:177], v[102:105]
	v_mfma_f32_16x16x32_bf16 v[98:101], v[158:161], v[174:177], v[98:101]
	v_mfma_f32_16x16x32_bf16 v[86:89], v[150:153], v[182:185], v[86:89]
	v_mfma_f32_16x16x32_bf16 v[82:85], v[158:161], v[182:185], v[82:85]
	v_mfma_f32_16x16x32_bf16 v[70:73], v[150:153], v[190:193], v[70:73]
	v_mfma_f32_16x16x32_bf16 v[66:69], v[158:161], v[190:193], v[66:69]
	s_barrier
	s_add_i32 s56, s57, s85
	v_lshl_add_u64 v[194:195], s[74:75], 0, v[32:33]
	s_mov_b32 m0, s56
	ds_read_b128 v[162:165], v230 offset:16384
	ds_read_b128 v[166:169], v230 offset:17408
	ds_read_b128 v[170:173], v230 offset:18432
	ds_read_b128 v[174:177], v230 offset:19456
	ds_read_b128 v[178:181], v230 offset:20480
	ds_read_b128 v[182:185], v230 offset:21504
	ds_read_b128 v[186:189], v230 offset:22528
	ds_read_b128 v[190:193], v230 offset:23552
	global_load_lds_dwordx4 v[194:195], off
	s_add_i32 m0, s56, 0x2000
	s_add_u32 s56, s74, 0x40000
	v_lshl_add_u64 v[206:207], s[74:75], 0, v[196:197]
	s_addc_u32 s57, s75, 0
	s_add_i32 s9, s9, s85
	global_load_lds_dwordx4 v[206:207], off
	v_lshl_add_u64 v[208:209], s[56:57], 0, v[32:33]
	s_mov_b32 m0, s9
	v_lshl_add_u64 v[210:211], vcc, 0, v[198:199]
	global_load_lds_dwordx4 v[208:209], off
	v_lshl_add_u64 v[208:209], s[56:57], 0, v[196:197]
	s_add_i32 m0, s9, 0x2000
	s_nop 0
	global_load_lds_dwordx4 v[208:209], off
	v_lshl_add_u64 v[208:209], vcc, 0, v[200:201]
	s_mov_b32 m0, s86
	s_nop 0
	global_load_lds_dwordx4 v[208:209], off
	s_mov_b32 m0, s87
	s_nop 0
	global_load_lds_dwordx4 v[210:211], off
	s_waitcnt vmcnt(8)
	s_waitcnt lgkmcnt(0)
	s_barrier
	s_waitcnt lgkmcnt(0)
	v_mfma_f32_16x16x32_bf16 v[62:65], v[122:125], v[162:165], v[62:65]
	v_mfma_f32_16x16x32_bf16 v[58:61], v[138:141], v[162:165], v[58:61]
	v_mfma_f32_16x16x32_bf16 v[46:49], v[122:125], v[170:173], v[46:49]
	v_mfma_f32_16x16x32_bf16 v[42:45], v[138:141], v[170:173], v[42:45]
	v_mfma_f32_16x16x32_bf16 v[28:31], v[122:125], v[178:181], v[28:31]
	v_mfma_f32_16x16x32_bf16 v[24:27], v[138:141], v[178:181], v[24:27]
	v_mfma_f32_16x16x32_bf16 v[12:15], v[122:125], v[186:189], v[12:15]
	v_mfma_f32_16x16x32_bf16 v[8:11], v[138:141], v[186:189], v[8:11]
	v_mfma_f32_16x16x32_bf16 v[62:65], v[134:137], v[166:169], v[62:65]
	v_mfma_f32_16x16x32_bf16 v[58:61], v[142:145], v[166:169], v[58:61]
	v_mfma_f32_16x16x32_bf16 v[46:49], v[134:137], v[174:177], v[46:49]
	v_mfma_f32_16x16x32_bf16 v[42:45], v[142:145], v[174:177], v[42:45]
	v_mfma_f32_16x16x32_bf16 v[28:31], v[134:137], v[182:185], v[28:31]
	v_mfma_f32_16x16x32_bf16 v[24:27], v[142:145], v[182:185], v[24:27]
	v_mfma_f32_16x16x32_bf16 v[12:15], v[134:137], v[190:193], v[12:15]
	v_mfma_f32_16x16x32_bf16 v[8:11], v[142:145], v[190:193], v[8:11]
	v_mfma_f32_16x16x32_bf16 v[54:57], v[146:149], v[162:165], v[54:57]
	v_mfma_f32_16x16x32_bf16 v[50:53], v[154:157], v[162:165], v[50:53]
	v_mfma_f32_16x16x32_bf16 v[38:41], v[146:149], v[170:173], v[38:41]
	v_mfma_f32_16x16x32_bf16 v[34:37], v[154:157], v[170:173], v[34:37]
	v_mfma_f32_16x16x32_bf16 v[20:23], v[146:149], v[178:181], v[20:23]
	v_mfma_f32_16x16x32_bf16 v[16:19], v[154:157], v[178:181], v[16:19]
	v_mfma_f32_16x16x32_bf16 v[4:7], v[146:149], v[186:189], v[4:7]
	v_mfma_f32_16x16x32_bf16 v[0:3], v[154:157], v[186:189], v[0:3]
	v_mfma_f32_16x16x32_bf16 v[54:57], v[150:153], v[166:169], v[54:57]
	v_mfma_f32_16x16x32_bf16 v[50:53], v[158:161], v[166:169], v[50:53]
	v_mfma_f32_16x16x32_bf16 v[38:41], v[150:153], v[174:177], v[38:41]
	v_mfma_f32_16x16x32_bf16 v[34:37], v[158:161], v[174:177], v[34:37]
	v_mfma_f32_16x16x32_bf16 v[20:23], v[150:153], v[182:185], v[20:23]
	v_mfma_f32_16x16x32_bf16 v[16:19], v[158:161], v[182:185], v[16:19]
	v_mfma_f32_16x16x32_bf16 v[4:7], v[150:153], v[190:193], v[4:7]
	v_mfma_f32_16x16x32_bf16 v[0:3], v[158:161], v[190:193], v[0:3]
	s_barrier
	s_add_i32 s9, 0, 0x18000
	s_add_i32 s64, 0, 0x1c000
	v_add_u32_e32 v142, s9, v228
	v_add_u32_e32 v158, s64, v228
	ds_read_b128 v[122:125], v142
	ds_read_b128 v[134:137], v142 offset:1024
	ds_read_b128 v[138:141], v142 offset:2048
	ds_read_b128 v[142:145], v142 offset:3072
	ds_read_b128 v[146:149], v158
	ds_read_b128 v[150:153], v158 offset:1024
	ds_read_b128 v[154:157], v158 offset:2048
	ds_read_b128 v[158:161], v158 offset:3072
	s_add_u32 s56, vcc_lo, 0x40000
	s_addc_u32 s57, vcc_hi, 0
	s_mov_b32 m0, s88
	v_lshl_add_u64 v[212:213], s[56:57], 0, v[200:201]
	ds_read_b128 v[162:165], v230 offset:32768
	ds_read_b128 v[166:169], v230 offset:33792
	ds_read_b128 v[170:173], v230 offset:34816
	ds_read_b128 v[174:177], v230 offset:35840
	ds_read_b128 v[178:181], v230 offset:36864
	ds_read_b128 v[182:185], v230 offset:37888
	ds_read_b128 v[186:189], v230 offset:38912
	ds_read_b128 v[190:193], v230 offset:39936
	global_load_lds_dwordx4 v[212:213], off
	v_lshl_add_u64 v[212:213], s[56:57], 0, v[198:199]
	s_mov_b32 m0, s89
	s_nop 0
	global_load_lds_dwordx4 v[212:213], off
	s_waitcnt vmcnt(8)
	s_waitcnt lgkmcnt(0)
	s_barrier
	s_waitcnt lgkmcnt(0)
	v_mfma_f32_16x16x32_bf16 v[130:133], v[122:125], v[162:165], v[130:133]
	v_mfma_f32_16x16x32_bf16 v[126:129], v[138:141], v[162:165], v[126:129]
	v_mfma_f32_16x16x32_bf16 v[110:113], v[122:125], v[170:173], v[110:113]
	v_mfma_f32_16x16x32_bf16 v[106:109], v[138:141], v[170:173], v[106:109]
	v_mfma_f32_16x16x32_bf16 v[94:97], v[122:125], v[178:181], v[94:97]
	v_mfma_f32_16x16x32_bf16 v[90:93], v[138:141], v[178:181], v[90:93]
	v_mfma_f32_16x16x32_bf16 v[78:81], v[122:125], v[186:189], v[78:81]
	v_mfma_f32_16x16x32_bf16 v[74:77], v[138:141], v[186:189], v[74:77]
	v_mfma_f32_16x16x32_bf16 v[130:133], v[134:137], v[166:169], v[130:133]
	v_mfma_f32_16x16x32_bf16 v[126:129], v[142:145], v[166:169], v[126:129]
	v_mfma_f32_16x16x32_bf16 v[110:113], v[134:137], v[174:177], v[110:113]
	v_mfma_f32_16x16x32_bf16 v[106:109], v[142:145], v[174:177], v[106:109]
	v_mfma_f32_16x16x32_bf16 v[94:97], v[134:137], v[182:185], v[94:97]
	v_mfma_f32_16x16x32_bf16 v[90:93], v[142:145], v[182:185], v[90:93]
	v_mfma_f32_16x16x32_bf16 v[78:81], v[134:137], v[190:193], v[78:81]
	v_mfma_f32_16x16x32_bf16 v[74:77], v[142:145], v[190:193], v[74:77]
	v_mfma_f32_16x16x32_bf16 v[118:121], v[146:149], v[162:165], v[118:121]
	v_mfma_f32_16x16x32_bf16 v[114:117], v[154:157], v[162:165], v[114:117]
	v_mfma_f32_16x16x32_bf16 v[102:105], v[146:149], v[170:173], v[102:105]
	v_mfma_f32_16x16x32_bf16 v[98:101], v[154:157], v[170:173], v[98:101]
	v_mfma_f32_16x16x32_bf16 v[86:89], v[146:149], v[178:181], v[86:89]
	v_mfma_f32_16x16x32_bf16 v[82:85], v[154:157], v[178:181], v[82:85]
	v_mfma_f32_16x16x32_bf16 v[70:73], v[146:149], v[186:189], v[70:73]
	v_mfma_f32_16x16x32_bf16 v[66:69], v[154:157], v[186:189], v[66:69]
	v_mfma_f32_16x16x32_bf16 v[118:121], v[150:153], v[166:169], v[118:121]
	v_mfma_f32_16x16x32_bf16 v[114:117], v[158:161], v[166:169], v[114:117]
	v_mfma_f32_16x16x32_bf16 v[102:105], v[150:153], v[174:177], v[102:105]
	v_mfma_f32_16x16x32_bf16 v[98:101], v[158:161], v[174:177], v[98:101]
	v_mfma_f32_16x16x32_bf16 v[86:89], v[150:153], v[182:185], v[86:89]
	v_mfma_f32_16x16x32_bf16 v[82:85], v[158:161], v[182:185], v[82:85]
	v_mfma_f32_16x16x32_bf16 v[70:73], v[150:153], v[190:193], v[70:73]
	v_mfma_f32_16x16x32_bf16 v[66:69], v[158:161], v[190:193], v[66:69]
	s_barrier
	s_add_i32 s9, s9, s85
	v_lshl_add_u64 v[194:195], v[194:195], 0, s[38:39]
	s_mov_b32 m0, s9
	ds_read_b128 v[162:165], v230 offset:49152
	ds_read_b128 v[166:169], v230 offset:50176
	ds_read_b128 v[170:173], v230 offset:51200
	ds_read_b128 v[174:177], v230 offset:52224
	ds_read_b128 v[178:181], v230 offset:53248
	ds_read_b128 v[182:185], v230 offset:54272
	ds_read_b128 v[186:189], v230 offset:55296
	ds_read_b128 v[190:193], v230 offset:56320
	global_load_lds_dwordx4 v[194:195], off
	s_add_i32 m0, s9, 0x2000
	s_add_u32 s56, s74, 0x40080
	v_lshl_add_u64 v[194:195], v[206:207], 0, s[38:39]
	s_addc_u32 s57, s75, 0
	s_add_i32 s9, s64, s85
	global_load_lds_dwordx4 v[194:195], off
	v_lshl_add_u64 v[194:195], s[56:57], 0, v[32:33]
	s_mov_b32 m0, s9
	s_nop 0
	global_load_lds_dwordx4 v[194:195], off
	v_lshl_add_u64 v[194:195], s[56:57], 0, v[196:197]
	s_add_i32 m0, s9, 0x2000
	s_nop 0
	global_load_lds_dwordx4 v[194:195], off
	v_lshl_add_u64 v[194:195], v[208:209], 0, s[38:39]
	s_mov_b32 m0, s28
	s_nop 0
	global_load_lds_dwordx4 v[194:195], off
	v_lshl_add_u64 v[194:195], v[210:211], 0, s[38:39]
	s_mov_b32 m0, s90
	s_nop 0
	global_load_lds_dwordx4 v[194:195], off
	s_waitcnt vmcnt(8)
	s_waitcnt lgkmcnt(0)
	s_barrier
	s_waitcnt lgkmcnt(0)
	v_mfma_f32_16x16x32_bf16 v[62:65], v[122:125], v[162:165], v[62:65]
	v_mfma_f32_16x16x32_bf16 v[58:61], v[138:141], v[162:165], v[58:61]
	v_mfma_f32_16x16x32_bf16 v[46:49], v[122:125], v[170:173], v[46:49]
	v_mfma_f32_16x16x32_bf16 v[42:45], v[138:141], v[170:173], v[42:45]
	v_mfma_f32_16x16x32_bf16 v[28:31], v[122:125], v[178:181], v[28:31]
	v_mfma_f32_16x16x32_bf16 v[24:27], v[138:141], v[178:181], v[24:27]
	v_mfma_f32_16x16x32_bf16 v[12:15], v[122:125], v[186:189], v[12:15]
	v_mfma_f32_16x16x32_bf16 v[8:11], v[138:141], v[186:189], v[8:11]
	v_mfma_f32_16x16x32_bf16 v[62:65], v[134:137], v[166:169], v[62:65]
	v_mfma_f32_16x16x32_bf16 v[58:61], v[142:145], v[166:169], v[58:61]
	v_mfma_f32_16x16x32_bf16 v[46:49], v[134:137], v[174:177], v[46:49]
	v_mfma_f32_16x16x32_bf16 v[42:45], v[142:145], v[174:177], v[42:45]
	v_mfma_f32_16x16x32_bf16 v[28:31], v[134:137], v[182:185], v[28:31]
	v_mfma_f32_16x16x32_bf16 v[24:27], v[142:145], v[182:185], v[24:27]
	v_mfma_f32_16x16x32_bf16 v[12:15], v[134:137], v[190:193], v[12:15]
	v_mfma_f32_16x16x32_bf16 v[8:11], v[142:145], v[190:193], v[8:11]
	v_mfma_f32_16x16x32_bf16 v[54:57], v[146:149], v[162:165], v[54:57]
	v_mfma_f32_16x16x32_bf16 v[50:53], v[154:157], v[162:165], v[50:53]
	v_mfma_f32_16x16x32_bf16 v[38:41], v[146:149], v[170:173], v[38:41]
	v_mfma_f32_16x16x32_bf16 v[34:37], v[154:157], v[170:173], v[34:37]
	v_mfma_f32_16x16x32_bf16 v[20:23], v[146:149], v[178:181], v[20:23]
	v_mfma_f32_16x16x32_bf16 v[16:19], v[154:157], v[178:181], v[16:19]
	v_mfma_f32_16x16x32_bf16 v[4:7], v[146:149], v[186:189], v[4:7]
	v_mfma_f32_16x16x32_bf16 v[0:3], v[154:157], v[186:189], v[0:3]
	v_mfma_f32_16x16x32_bf16 v[54:57], v[150:153], v[166:169], v[54:57]
	v_mfma_f32_16x16x32_bf16 v[50:53], v[158:161], v[166:169], v[50:53]
	v_mfma_f32_16x16x32_bf16 v[38:41], v[150:153], v[174:177], v[38:41]
	v_mfma_f32_16x16x32_bf16 v[34:37], v[158:161], v[174:177], v[34:37]
	v_mfma_f32_16x16x32_bf16 v[20:23], v[150:153], v[182:185], v[20:23]
	v_mfma_f32_16x16x32_bf16 v[16:19], v[158:161], v[182:185], v[16:19]
	v_mfma_f32_16x16x32_bf16 v[4:7], v[150:153], v[190:193], v[4:7]
	v_mfma_f32_16x16x32_bf16 v[0:3], v[158:161], v[190:193], v[0:3]
	s_barrier
	s_add_i32 s8, s8, 2
	s_add_u32 s14, s14, 0x100
	s_addc_u32 s15, s15, 0
	s_add_u32 s96, s96, 0x100
	s_addc_u32 s97, s97, 0
	s_cmp_gt_u32 s8, 13
	s_cbranch_scc0 .LBB0_1640
	s_and_b64 vcc, exec, s[34:35]
	s_cbranch_vccz .LBB0_1643
	s_barrier
